# K-loop arbitration: the computing wave reaches its closing s_barrier before dropping priority (s_barrier then s_setprio 0)
# speedup vs baseline: 1.0041x; 1.0041x over previous
; #define PG8_STAGE(bufoff, gbase, voff) do { _Pragma("unroll") for (int _i = 0; _i < 2; ++_i) \
;         __builtin_amdgcn_global_load_lds((const unsigned*)((const char*)(gbase) + (voff)[_i]), (PG8_LAS unsigned*)(lds + (bufoff) + ldsw + _i * 8192), 16, 0, 0); } while (0)
; #define PG8_LDA(dst, b, h) do { _Pragma("unroll") for (int m = 0; m < 4; ++m) _Pragma("unroll") for (int k = 0; k < 2; ++k) dst[m][k] = *(const PG8_LAS bf16x8*)(lds + PG8_SA(b, h) + aoff + m * 2048 + k * 1024); } while (0)
; #define PG8_LDB(dst, b, h) do { _Pragma("unroll") for (int n = 0; n < 2; ++n) _Pragma("unroll") for (int k = 0; k < 2; ++k) dst[n][k] = *(const PG8_LAS bf16x8*)(lds + PG8_SB(b, h) + boff + n * 2048 + k * 1024); } while (0)
; #define PG8_MMA(ai, bj, At, Bt) do { __builtin_amdgcn_s_setprio(1); _Pragma("unroll") for (int m = 0; m < 4; ++m) _Pragma("unroll") for (int n = 0; n < 2; ++n) _Pragma("unroll") for (int k = 0; k < 2; ++k) \
;         acc[ai][bj][m][n] = __builtin_amdgcn_mfma_f32_16x16x32_bf16(Bt[n][k], At[m][k], acc[ai][bj][m][n], 0, 0, 0); __builtin_amdgcn_s_setprio(0); } while (0)
; template <class Epi, class Sched, bool ALIGN_EPI = false, bool SP2 = false>
; __device__ __forceinline__ void gemm_phase(PG8_LAS unsigned char* lds, const Gemm g, const Sched& S, const Epi& E) {
;     ...
;             PG8_LDB(B0, 0, 0); PG8_LDB(B1, 0, 1); PG8_SCHED; PG8_LDA(At, 0, 0); PG8_STAGE(PG8_SA(1, 1), a1 + hstep, voffA);
;             PG8_WAIT_V(8); PG8_WAIT_L(0); PG8_BAR; PG8_MMA(0, 0, At, B0); PG8_MMA(0, 1, At, B1); PG8_BAR; PG8_SCHED;
;             if (full) PG8_LDA(At, 0, 1); PG8_STAGE(PG8_SB(0, 0), b2, voffB); PG8_STAGE(PG8_SB(0, 1), b2 + hstep, voffB); PG8_STAGE(PG8_SA(0, 0), a2, voffA);
;             PG8_WAIT_V(8); PG8_WAIT_L(0); PG8_BAR; if (full) { PG8_MMA(1, 0, At, B0); PG8_MMA(1, 1, At, B1); } PG8_BAR; PG8_SCHED;
;             PG8_LDB(B0, 1, 0); PG8_LDB(B1, 1, 1); PG8_SCHED; PG8_LDA(At, 1, 0); PG8_STAGE(PG8_SA(0, 1), a2 + hstep, voffA);
;             PG8_WAIT_V(8); PG8_WAIT_L(0); PG8_BAR; PG8_MMA(0, 0, At, B0); PG8_MMA(0, 1, At, B1); PG8_BAR; PG8_SCHED;
;             if (full) PG8_LDA(At, 1, 1); PG8_STAGE(PG8_SB(1, 0), b3, voffB); PG8_STAGE(PG8_SB(1, 1), b3 + hstep, voffB); PG8_STAGE(PG8_SA(1, 0), a3, voffA);
;             PG8_WAIT_V(8); PG8_WAIT_L(0); PG8_BAR; if (full) { PG8_MMA(1, 0, At, B0); PG8_MMA(1, 1, At, B1); } PG8_BAR; PG8_SCHED;
.LBB0_291:
	s_barrier
	s_setprio 0
	s_add_i32 s89, s89, 2
	s_add_u32 s36, s36, 0x100
	s_addc_u32 s37, s37, 0
	s_add_u32 s83, s83, 0x100
	s_addc_u32 s88, s88, 0
	s_cmp_gt_u32 s89, 13
	s_cbranch_scc1 .LBB0_300
.LBB0_292:
	v_add_u32_e32 v0, 0x10000, v223
	ds_read_b128 v[148:151], v0
	ds_read_b128 v[152:155], v0 offset:1024
	ds_read_b128 v[156:159], v0 offset:2048
	ds_read_b128 v[160:163], v0 offset:3072
	v_add_u32_e32 v0, 0x14000, v223
	ds_read_b128 v[132:135], v0
	ds_read_b128 v[136:139], v0 offset:1024
	ds_read_b128 v[140:143], v0 offset:2048
	ds_read_b128 v[144:147], v0 offset:3072
	v_lshl_add_u64 v[2:3], s[36:37], 0, v[204:205]
	s_add_i32 m0, s31, 0xc000
	ds_read_b128 v[176:179], v224
	ds_read_b128 v[192:195], v224 offset:1024
	ds_read_b128 v[172:175], v224 offset:2048
	ds_read_b128 v[188:191], v224 offset:3072
	ds_read_b128 v[168:171], v224 offset:4096
	ds_read_b128 v[184:187], v224 offset:5120
	ds_read_b128 v[164:167], v224 offset:6144
	ds_read_b128 v[180:183], v224 offset:7168
	global_load_lds_dwordx4 v[2:3], off
	v_lshl_add_u64 v[2:3], s[36:37], 0, v[206:207]
	s_add_i32 m0, s31, 0xe000
	s_nop 0
	global_load_lds_dwordx4 v[2:3], off
	s_waitcnt vmcnt(8)
	s_waitcnt lgkmcnt(0)
	s_barrier
	s_setprio 1
	s_waitcnt lgkmcnt(0)
	v_mfma_f32_16x16x32_bf16 v[128:131], v[148:151], v[176:179], v[128:131]
	v_mfma_f32_16x16x32_bf16 v[124:127], v[156:159], v[176:179], v[124:127]
	v_mfma_f32_16x16x32_bf16 v[112:115], v[148:151], v[172:175], v[112:115]
	v_mfma_f32_16x16x32_bf16 v[108:111], v[156:159], v[172:175], v[108:111]
	v_mfma_f32_16x16x32_bf16 v[96:99], v[148:151], v[168:171], v[96:99]
	v_mfma_f32_16x16x32_bf16 v[92:95], v[156:159], v[168:171], v[92:95]
	v_mfma_f32_16x16x32_bf16 v[80:83], v[148:151], v[164:167], v[80:83]
	v_mfma_f32_16x16x32_bf16 v[76:79], v[156:159], v[164:167], v[76:79]
	v_mfma_f32_16x16x32_bf16 v[128:131], v[152:155], v[192:195], v[128:131]
	v_mfma_f32_16x16x32_bf16 v[124:127], v[160:163], v[192:195], v[124:127]
	v_mfma_f32_16x16x32_bf16 v[112:115], v[152:155], v[188:191], v[112:115]
	v_mfma_f32_16x16x32_bf16 v[108:111], v[160:163], v[188:191], v[108:111]
	v_mfma_f32_16x16x32_bf16 v[96:99], v[152:155], v[184:187], v[96:99]
	v_mfma_f32_16x16x32_bf16 v[92:95], v[160:163], v[184:187], v[92:95]
	v_mfma_f32_16x16x32_bf16 v[80:83], v[152:155], v[180:183], v[80:83]
	v_mfma_f32_16x16x32_bf16 v[76:79], v[160:163], v[180:183], v[76:79]
	s_setprio 0
	s_setprio 1
	v_mfma_f32_16x16x32_bf16 v[120:123], v[132:135], v[176:179], v[120:123]
	v_mfma_f32_16x16x32_bf16 v[116:119], v[140:143], v[176:179], v[116:119]
	v_mfma_f32_16x16x32_bf16 v[104:107], v[132:135], v[172:175], v[104:107]
	v_mfma_f32_16x16x32_bf16 v[100:103], v[140:143], v[172:175], v[100:103]
	v_mfma_f32_16x16x32_bf16 v[88:91], v[132:135], v[168:171], v[88:91]
	v_mfma_f32_16x16x32_bf16 v[84:87], v[140:143], v[168:171], v[84:87]
	v_mfma_f32_16x16x32_bf16 v[72:75], v[132:135], v[164:167], v[72:75]
	v_mfma_f32_16x16x32_bf16 v[68:71], v[140:143], v[164:167], v[68:71]
	v_mfma_f32_16x16x32_bf16 v[120:123], v[136:139], v[192:195], v[120:123]
	v_mfma_f32_16x16x32_bf16 v[116:119], v[144:147], v[192:195], v[116:119]
	v_mfma_f32_16x16x32_bf16 v[104:107], v[136:139], v[188:191], v[104:107]
	v_mfma_f32_16x16x32_bf16 v[100:103], v[144:147], v[188:191], v[100:103]
	v_mfma_f32_16x16x32_bf16 v[88:91], v[136:139], v[184:187], v[88:91]
	v_mfma_f32_16x16x32_bf16 v[84:87], v[144:147], v[184:187], v[84:87]
	v_mfma_f32_16x16x32_bf16 v[72:75], v[136:139], v[180:183], v[72:75]
	v_mfma_f32_16x16x32_bf16 v[68:71], v[144:147], v[180:183], v[68:71]
	s_barrier
	s_setprio 0
	v_cndmask_b32_e64 v0, 0, 1, s[34:35]
	v_cmp_ne_u32_e64 s[4:5], 1, v0
	s_andn2_b64 vcc, exec, s[34:35]
	s_cbranch_vccnz .LBB0_294
	ds_read_b128 v[176:179], v224 offset:16384
	ds_read_b128 v[192:195], v224 offset:17408
	ds_read_b128 v[172:175], v224 offset:18432
	ds_read_b128 v[188:191], v224 offset:19456
	ds_read_b128 v[168:171], v224 offset:20480
	ds_read_b128 v[184:187], v224 offset:21504
	ds_read_b128 v[164:167], v224 offset:22528
	ds_read_b128 v[180:183], v224 offset:23552

; #define PG8_STAGE(bufoff, gbase, voff) do { _Pragma("unroll") for (int _i = 0; _i < 2; ++_i) \
;         __builtin_amdgcn_global_load_lds((const unsigned*)((const char*)(gbase) + (voff)[_i]), (PG8_LAS unsigned*)(lds + (bufoff) + ldsw + _i * 8192), 16, 0, 0); } while (0)
; #define PG8_LDA(dst, b, h) do { _Pragma("unroll") for (int m = 0; m < 4; ++m) _Pragma("unroll") for (int k = 0; k < 2; ++k) dst[m][k] = *(const PG8_LAS bf16x8*)(lds + PG8_SA(b, h) + aoff + m * 2048 + k * 1024); } while (0)
; #define PG8_LDB(dst, b, h) do { _Pragma("unroll") for (int n = 0; n < 2; ++n) _Pragma("unroll") for (int k = 0; k < 2; ++k) dst[n][k] = *(const PG8_LAS bf16x8*)(lds + PG8_SB(b, h) + boff + n * 2048 + k * 1024); } while (0)
; #define PG8_MMA(ai, bj, At, Bt) do { __builtin_amdgcn_s_setprio(1); _Pragma("unroll") for (int m = 0; m < 4; ++m) _Pragma("unroll") for (int n = 0; n < 2; ++n) _Pragma("unroll") for (int k = 0; k < 2; ++k) \
;         acc[ai][bj][m][n] = __builtin_amdgcn_mfma_f32_16x16x32_bf16(Bt[n][k], At[m][k], acc[ai][bj][m][n], 0, 0, 0); __builtin_amdgcn_s_setprio(0); } while (0)
; template <class Epi, class Sched, bool ALIGN_EPI = false, bool SP2 = false>
; __device__ __forceinline__ void gemm_phase(PG8_LAS unsigned char* lds, const Gemm g, const Sched& S, const Epi& E) {
;     ...
;             PG8_LDB(B0, 0, 0); PG8_LDB(B1, 0, 1); PG8_SCHED; PG8_LDA(At, 0, 0); PG8_STAGE(PG8_SA(1, 1), a1 + hstep, voffA);
;             PG8_WAIT_V(8); PG8_WAIT_L(0); PG8_BAR; PG8_MMA(0, 0, At, B0); PG8_MMA(0, 1, At, B1); PG8_BAR; PG8_SCHED;
;             if (full) PG8_LDA(At, 0, 1); PG8_STAGE(PG8_SB(0, 0), b2, voffB); PG8_STAGE(PG8_SB(0, 1), b2 + hstep, voffB); PG8_STAGE(PG8_SA(0, 0), a2, voffA);
;             PG8_WAIT_V(8); PG8_WAIT_L(0); PG8_BAR; if (full) { PG8_MMA(1, 0, At, B0); PG8_MMA(1, 1, At, B1); } PG8_BAR; PG8_SCHED;
;             PG8_LDB(B0, 1, 0); PG8_LDB(B1, 1, 1); PG8_SCHED; PG8_LDA(At, 1, 0); PG8_STAGE(PG8_SA(0, 1), a2 + hstep, voffA);
;             PG8_WAIT_V(8); PG8_WAIT_L(0); PG8_BAR; PG8_MMA(0, 0, At, B0); PG8_MMA(0, 1, At, B1); PG8_BAR; PG8_SCHED;
;             if (full) PG8_LDA(At, 1, 1); PG8_STAGE(PG8_SB(1, 0), b3, voffB); PG8_STAGE(PG8_SB(1, 1), b3 + hstep, voffB); PG8_STAGE(PG8_SA(1, 0), a3, voffA);
;             PG8_WAIT_V(8); PG8_WAIT_L(0); PG8_BAR; if (full) { PG8_MMA(1, 0, At, B0); PG8_MMA(1, 1, At, B1); } PG8_BAR; PG8_SCHED;
.LBB0_296:
	s_barrier
	s_setprio 0
	v_add_u32_e32 v0, 0x18000, v223
	ds_read_b128 v[148:151], v0
	ds_read_b128 v[152:155], v0 offset:1024
	ds_read_b128 v[156:159], v0 offset:2048
	ds_read_b128 v[160:163], v0 offset:3072
	v_add_u32_e32 v0, 0x1c000, v223
	ds_read_b128 v[132:135], v0
	ds_read_b128 v[136:139], v0 offset:1024
	ds_read_b128 v[140:143], v0 offset:2048
	ds_read_b128 v[144:147], v0 offset:3072
	s_add_u32 s42, s42, 0x40000
	s_addc_u32 s43, s43, 0
	s_mov_b32 m0, s59
	v_lshl_add_u64 v[212:213], s[42:43], 0, v[196:197]
	ds_read_b128 v[176:179], v224 offset:32768
	ds_read_b128 v[192:195], v224 offset:33792
	ds_read_b128 v[172:175], v224 offset:34816
	ds_read_b128 v[188:191], v224 offset:35840
	ds_read_b128 v[168:171], v224 offset:36864
	ds_read_b128 v[184:187], v224 offset:37888
	ds_read_b128 v[164:167], v224 offset:38912
	ds_read_b128 v[180:183], v224 offset:39936
	global_load_lds_dwordx4 v[212:213], off
	v_lshl_add_u64 v[212:213], s[42:43], 0, v[200:201]
	s_mov_b32 m0, s60
	s_nop 0
	global_load_lds_dwordx4 v[212:213], off
	s_waitcnt vmcnt(8)
	s_waitcnt lgkmcnt(0)
	s_barrier
	s_setprio 1
	s_waitcnt lgkmcnt(0)
	v_mfma_f32_16x16x32_bf16 v[128:131], v[148:151], v[176:179], v[128:131]
	v_mfma_f32_16x16x32_bf16 v[124:127], v[156:159], v[176:179], v[124:127]
	v_mfma_f32_16x16x32_bf16 v[112:115], v[148:151], v[172:175], v[112:115]
	v_mfma_f32_16x16x32_bf16 v[108:111], v[156:159], v[172:175], v[108:111]
	v_mfma_f32_16x16x32_bf16 v[96:99], v[148:151], v[168:171], v[96:99]
	v_mfma_f32_16x16x32_bf16 v[92:95], v[156:159], v[168:171], v[92:95]
	v_mfma_f32_16x16x32_bf16 v[80:83], v[148:151], v[164:167], v[80:83]
	v_mfma_f32_16x16x32_bf16 v[76:79], v[156:159], v[164:167], v[76:79]
	v_mfma_f32_16x16x32_bf16 v[128:131], v[152:155], v[192:195], v[128:131]
	v_mfma_f32_16x16x32_bf16 v[124:127], v[160:163], v[192:195], v[124:127]
	v_mfma_f32_16x16x32_bf16 v[112:115], v[152:155], v[188:191], v[112:115]
	v_mfma_f32_16x16x32_bf16 v[108:111], v[160:163], v[188:191], v[108:111]
	v_mfma_f32_16x16x32_bf16 v[96:99], v[152:155], v[184:187], v[96:99]
	v_mfma_f32_16x16x32_bf16 v[92:95], v[160:163], v[184:187], v[92:95]
	v_mfma_f32_16x16x32_bf16 v[80:83], v[152:155], v[180:183], v[80:83]
	v_mfma_f32_16x16x32_bf16 v[76:79], v[160:163], v[180:183], v[76:79]
	s_setprio 0
	s_setprio 1
	v_mfma_f32_16x16x32_bf16 v[120:123], v[132:135], v[176:179], v[120:123]
	v_mfma_f32_16x16x32_bf16 v[116:119], v[140:143], v[176:179], v[116:119]
	v_mfma_f32_16x16x32_bf16 v[104:107], v[132:135], v[172:175], v[104:107]
	v_mfma_f32_16x16x32_bf16 v[100:103], v[140:143], v[172:175], v[100:103]
	v_mfma_f32_16x16x32_bf16 v[88:91], v[132:135], v[168:171], v[88:91]
	v_mfma_f32_16x16x32_bf16 v[84:87], v[140:143], v[168:171], v[84:87]
	v_mfma_f32_16x16x32_bf16 v[72:75], v[132:135], v[164:167], v[72:75]
	v_mfma_f32_16x16x32_bf16 v[68:71], v[140:143], v[164:167], v[68:71]
	v_mfma_f32_16x16x32_bf16 v[120:123], v[136:139], v[192:195], v[120:123]
	v_mfma_f32_16x16x32_bf16 v[116:119], v[144:147], v[192:195], v[116:119]
	v_mfma_f32_16x16x32_bf16 v[104:107], v[136:139], v[188:191], v[104:107]
	v_mfma_f32_16x16x32_bf16 v[100:103], v[144:147], v[188:191], v[100:103]
	v_mfma_f32_16x16x32_bf16 v[88:91], v[136:139], v[184:187], v[88:91]
	v_mfma_f32_16x16x32_bf16 v[84:87], v[144:147], v[184:187], v[84:87]
	v_mfma_f32_16x16x32_bf16 v[72:75], v[136:139], v[180:183], v[72:75]
	v_mfma_f32_16x16x32_bf16 v[68:71], v[144:147], v[180:183], v[68:71]
	s_barrier
	s_setprio 0
	s_and_b64 vcc, exec, s[4:5]
	s_cbranch_vccnz .LBB0_298
	ds_read_b128 v[176:179], v224 offset:49152
	ds_read_b128 v[192:195], v224 offset:50176
	ds_read_b128 v[172:175], v224 offset:51200
	ds_read_b128 v[188:191], v224 offset:52224
	ds_read_b128 v[168:171], v224 offset:53248
	ds_read_b128 v[184:187], v224 offset:54272
	ds_read_b128 v[164:167], v224 offset:55296
	ds_read_b128 v[180:183], v224 offset:56320
.LBB0_298:
	s_mov_b32 m0, s61
	v_lshl_add_u64 v[2:3], v[2:3], 0, s[52:53]
	s_add_u32 s38, s38, 0x40080
	global_load_lds_dwordx4 v[2:3], off
	v_lshl_add_u64 v[2:3], v[208:209], 0, s[52:53]
	s_mov_b32 m0, s62
	s_addc_u32 s39, s39, 0
	global_load_lds_dwordx4 v[2:3], off
	v_lshl_add_u64 v[2:3], s[38:39], 0, v[198:199]
	s_mov_b32 m0, s65
	s_and_b64 vcc, exec, s[4:5]
	global_load_lds_dwordx4 v[2:3], off
	v_lshl_add_u64 v[2:3], s[38:39], 0, v[202:203]
	s_mov_b32 m0, s68
	s_nop 0
	global_load_lds_dwordx4 v[2:3], off
	v_lshl_add_u64 v[2:3], v[210:211], 0, s[52:53]
	s_mov_b32 m0, s63
	s_nop 0
	global_load_lds_dwordx4 v[2:3], off
	v_lshl_add_u64 v[2:3], v[220:221], 0, s[52:53]
	s_mov_b32 m0, s64
	s_nop 0
	global_load_lds_dwordx4 v[2:3], off
	s_waitcnt vmcnt(8)
	s_waitcnt lgkmcnt(0)
	s_barrier
	s_cbranch_vccnz .LBB0_291
	s_setprio 1
	s_waitcnt lgkmcnt(0)
	v_mfma_f32_16x16x32_bf16 v[64:67], v[148:151], v[176:179], v[64:67]
	v_mfma_f32_16x16x32_bf16 v[56:59], v[156:159], v[176:179], v[56:59]
	v_mfma_f32_16x16x32_bf16 v[48:51], v[148:151], v[172:175], v[48:51]
	v_mfma_f32_16x16x32_bf16 v[40:43], v[156:159], v[172:175], v[40:43]
	v_mfma_f32_16x16x32_bf16 v[32:35], v[148:151], v[168:171], v[32:35]
	v_mfma_f32_16x16x32_bf16 v[24:27], v[156:159], v[168:171], v[24:27]
	v_mfma_f32_16x16x32_bf16 v[16:19], v[148:151], v[164:167], v[16:19]
	v_mfma_f32_16x16x32_bf16 v[8:11], v[156:159], v[164:167], v[8:11]
	v_mfma_f32_16x16x32_bf16 v[64:67], v[152:155], v[192:195], v[64:67]
	v_mfma_f32_16x16x32_bf16 v[56:59], v[160:163], v[192:195], v[56:59]
	v_mfma_f32_16x16x32_bf16 v[48:51], v[152:155], v[188:191], v[48:51]
	v_mfma_f32_16x16x32_bf16 v[40:43], v[160:163], v[188:191], v[40:43]
	v_mfma_f32_16x16x32_bf16 v[32:35], v[152:155], v[184:187], v[32:35]
	v_mfma_f32_16x16x32_bf16 v[24:27], v[160:163], v[184:187], v[24:27]
	v_mfma_f32_16x16x32_bf16 v[16:19], v[152:155], v[180:183], v[16:19]
	v_mfma_f32_16x16x32_bf16 v[8:11], v[160:163], v[180:183], v[8:11]
	s_setprio 0
	s_setprio 1
	v_mfma_f32_16x16x32_bf16 v[60:63], v[132:135], v[176:179], v[60:63]
	v_mfma_f32_16x16x32_bf16 v[52:55], v[140:143], v[176:179], v[52:55]
	v_mfma_f32_16x16x32_bf16 v[44:47], v[132:135], v[172:175], v[44:47]
	v_mfma_f32_16x16x32_bf16 v[36:39], v[140:143], v[172:175], v[36:39]
	v_mfma_f32_16x16x32_bf16 v[28:31], v[132:135], v[168:171], v[28:31]
	v_mfma_f32_16x16x32_bf16 v[20:23], v[140:143], v[168:171], v[20:23]
	v_mfma_f32_16x16x32_bf16 v[12:15], v[132:135], v[164:167], v[12:15]
	v_mfma_f32_16x16x32_bf16 v[2:5], v[140:143], v[164:167], v[4:7]
	v_mfma_f32_16x16x32_bf16 v[60:63], v[136:139], v[192:195], v[60:63]
	v_mfma_f32_16x16x32_bf16 v[52:55], v[144:147], v[192:195], v[52:55]
	v_mfma_f32_16x16x32_bf16 v[44:47], v[136:139], v[188:191], v[44:47]
	v_mfma_f32_16x16x32_bf16 v[36:39], v[144:147], v[188:191], v[36:39]
	v_mfma_f32_16x16x32_bf16 v[28:31], v[136:139], v[184:187], v[28:31]
	v_mfma_f32_16x16x32_bf16 v[20:23], v[144:147], v[184:187], v[20:23]
	v_mfma_f32_16x16x32_bf16 v[12:15], v[136:139], v[180:183], v[12:15]
	v_mfma_f32_16x16x32_bf16 v[4:7], v[144:147], v[180:183], v[2:5]
	s_branch .LBB0_291

; #define PG8_STAGE(bufoff, gbase, voff) do { _Pragma("unroll") for (int _i = 0; _i < 2; ++_i) \
;         __builtin_amdgcn_global_load_lds((const unsigned*)((const char*)(gbase) + (voff)[_i]), (PG8_LAS unsigned*)(lds + (bufoff) + ldsw + _i * 8192), 16, 0, 0); } while (0)
; #define PG8_LDA(dst, b, h) do { _Pragma("unroll") for (int m = 0; m < 4; ++m) _Pragma("unroll") for (int k = 0; k < 2; ++k) dst[m][k] = *(const PG8_LAS bf16x8*)(lds + PG8_SA(b, h) + aoff + m * 2048 + k * 1024); } while (0)
; #define PG8_LDB(dst, b, h) do { _Pragma("unroll") for (int n = 0; n < 2; ++n) _Pragma("unroll") for (int k = 0; k < 2; ++k) dst[n][k] = *(const PG8_LAS bf16x8*)(lds + PG8_SB(b, h) + boff + n * 2048 + k * 1024); } while (0)
; #define PG8_MMA(ai, bj, At, Bt) do { __builtin_amdgcn_s_setprio(1); _Pragma("unroll") for (int m = 0; m < 4; ++m) _Pragma("unroll") for (int n = 0; n < 2; ++n) _Pragma("unroll") for (int k = 0; k < 2; ++k) \
;         acc[ai][bj][m][n] = __builtin_amdgcn_mfma_f32_16x16x32_bf16(Bt[n][k], At[m][k], acc[ai][bj][m][n], 0, 0, 0); __builtin_amdgcn_s_setprio(0); } while (0)
; template <class Epi, class Sched, bool ALIGN_EPI = false, bool SP2 = false>
; __device__ __forceinline__ void gemm_phase(PG8_LAS unsigned char* lds, const Gemm g, const Sched& S, const Epi& E) {
;     ...
;             PG8_LDB(B0, 0, 0); PG8_LDB(B1, 0, 1); PG8_SCHED; PG8_LDA(At, 0, 0); PG8_STAGE(PG8_SA(1, 1), a1 + hstep, voffA);
;             PG8_WAIT_V(8); PG8_WAIT_L(0); PG8_BAR; PG8_MMA(0, 0, At, B0); PG8_MMA(0, 1, At, B1); PG8_BAR; PG8_SCHED;
;             if (full) PG8_LDA(At, 0, 1); PG8_STAGE(PG8_SB(0, 0), b2, voffB); PG8_STAGE(PG8_SB(0, 1), b2 + hstep, voffB); PG8_STAGE(PG8_SA(0, 0), a2, voffA);
;             PG8_WAIT_V(8); PG8_WAIT_L(0); PG8_BAR; if (full) { PG8_MMA(1, 0, At, B0); PG8_MMA(1, 1, At, B1); } PG8_BAR; PG8_SCHED;
;             PG8_LDB(B0, 1, 0); PG8_LDB(B1, 1, 1); PG8_SCHED; PG8_LDA(At, 1, 0); PG8_STAGE(PG8_SA(0, 1), a2 + hstep, voffA);
;             PG8_WAIT_V(8); PG8_WAIT_L(0); PG8_BAR; PG8_MMA(0, 0, At, B0); PG8_MMA(0, 1, At, B1); PG8_BAR; PG8_SCHED;
;             if (full) PG8_LDA(At, 1, 1); PG8_STAGE(PG8_SB(1, 0), b3, voffB); PG8_STAGE(PG8_SB(1, 1), b3 + hstep, voffB); PG8_STAGE(PG8_SA(1, 0), a3, voffA);
;             PG8_WAIT_V(8); PG8_WAIT_L(0); PG8_BAR; if (full) { PG8_MMA(1, 0, At, B0); PG8_MMA(1, 1, At, B1); } PG8_BAR; PG8_SCHED;
.LBB0_382:
	s_add_u32 s30, s24, s28
	s_addc_u32 s31, s25, s29
	s_add_u32 s30, s30, 0x100
	s_addc_u32 s31, s31, 0
	s_add_u32 s65, s62, s28
	s_addc_u32 s68, s63, s29
	s_add_i32 s69, 0, 0x10000
	s_cmpk_eq_i32 s28, 0x1500
	s_cselect_b32 s35, s27, s31
	s_cselect_b32 s34, s26, s30
	v_add_u32_e32 v146, s69, v140
	s_cselect_b32 s31, s9, s68
	s_cselect_b32 s30, s8, s65
	s_add_i32 s65, 0, 0x14000
	ds_read_b128 v[142:145], v146
	ds_read_b128 v[154:157], v146 offset:1024
	ds_read_b128 v[158:161], v146 offset:2048
	ds_read_b128 v[162:165], v146 offset:3072
	v_add_u32_e32 v146, s65, v140
	ds_read_b128 v[166:169], v146
	ds_read_b128 v[170:173], v146 offset:1024
	ds_read_b128 v[174:177], v146 offset:2048
	ds_read_b128 v[178:181], v146 offset:3072
	v_lshl_add_u64 v[146:147], v[136:137], 0, s[28:29]
	s_add_i32 m0, s44, 0xc000
	ds_read_b128 v[182:185], v141
	ds_read_b128 v[186:189], v141 offset:1024
	ds_read_b128 v[190:193], v141 offset:2048
	ds_read_b128 v[194:197], v141 offset:3072
	ds_read_b128 v[198:201], v141 offset:4096
	ds_read_b128 v[202:205], v141 offset:5120
	ds_read_b128 v[206:209], v141 offset:6144
	ds_read_b128 v[220:223], v141 offset:7168
	global_load_lds_dwordx4 v[146:147], off
	v_lshl_add_u64 v[146:147], v[138:139], 0, s[28:29]
	s_add_i32 m0, s44, 0xe000
	s_nop 0
	global_load_lds_dwordx4 v[146:147], off
	s_waitcnt vmcnt(8)
	s_waitcnt lgkmcnt(0)
	s_barrier
	s_setprio 1
	s_waitcnt lgkmcnt(0)
	v_mfma_f32_16x16x32_bf16 v[114:117], v[142:145], v[182:185], v[114:117]
	v_mfma_f32_16x16x32_bf16 v[82:85], v[158:161], v[182:185], v[82:85]
	v_mfma_f32_16x16x32_bf16 v[122:125], v[142:145], v[190:193], v[122:125]
	v_mfma_f32_16x16x32_bf16 v[94:97], v[158:161], v[190:193], v[94:97]
	v_mfma_f32_16x16x32_bf16 v[126:129], v[142:145], v[198:201], v[126:129]
	v_mfma_f32_16x16x32_bf16 v[106:109], v[158:161], v[198:201], v[106:109]
	v_mfma_f32_16x16x32_bf16 v[118:121], v[142:145], v[206:209], v[118:121]
	v_mfma_f32_16x16x32_bf16 v[110:113], v[158:161], v[206:209], v[110:113]
	v_mfma_f32_16x16x32_bf16 v[114:117], v[154:157], v[186:189], v[114:117]
	v_mfma_f32_16x16x32_bf16 v[82:85], v[162:165], v[186:189], v[82:85]
	v_mfma_f32_16x16x32_bf16 v[122:125], v[154:157], v[194:197], v[122:125]
	v_mfma_f32_16x16x32_bf16 v[94:97], v[162:165], v[194:197], v[94:97]
	v_mfma_f32_16x16x32_bf16 v[126:129], v[154:157], v[202:205], v[126:129]
	v_mfma_f32_16x16x32_bf16 v[106:109], v[162:165], v[202:205], v[106:109]
	v_mfma_f32_16x16x32_bf16 v[118:121], v[154:157], v[220:223], v[118:121]
	v_mfma_f32_16x16x32_bf16 v[110:113], v[162:165], v[220:223], v[110:113]
	s_setprio 0
	s_setprio 1
	v_mfma_f32_16x16x32_bf16 v[26:29], v[166:169], v[182:185], v[26:29]
	v_mfma_f32_16x16x32_bf16 v[2:5], v[174:177], v[182:185], v[2:5]
	v_mfma_f32_16x16x32_bf16 v[34:37], v[166:169], v[190:193], v[34:37]
	v_mfma_f32_16x16x32_bf16 v[6:9], v[174:177], v[190:193], v[6:9]
	v_mfma_f32_16x16x32_bf16 v[42:45], v[166:169], v[198:201], v[42:45]
	v_mfma_f32_16x16x32_bf16 v[10:13], v[174:177], v[198:201], v[10:13]
	v_mfma_f32_16x16x32_bf16 v[46:49], v[166:169], v[206:209], v[46:49]
	v_mfma_f32_16x16x32_bf16 v[14:17], v[174:177], v[206:209], v[14:17]
	v_mfma_f32_16x16x32_bf16 v[26:29], v[170:173], v[186:189], v[26:29]
	v_mfma_f32_16x16x32_bf16 v[2:5], v[178:181], v[186:189], v[2:5]
	v_mfma_f32_16x16x32_bf16 v[34:37], v[170:173], v[194:197], v[34:37]
	v_mfma_f32_16x16x32_bf16 v[6:9], v[178:181], v[194:197], v[6:9]
	v_mfma_f32_16x16x32_bf16 v[42:45], v[170:173], v[202:205], v[42:45]
	v_mfma_f32_16x16x32_bf16 v[10:13], v[178:181], v[202:205], v[10:13]
	v_mfma_f32_16x16x32_bf16 v[46:49], v[170:173], v[220:223], v[46:49]
	v_mfma_f32_16x16x32_bf16 v[14:17], v[178:181], v[220:223], v[14:17]
	s_barrier
	s_setprio 0
	s_add_i32 s68, s69, s43
	v_lshl_add_u64 v[146:147], s[30:31], 0, v[0:1]
	s_mov_b32 m0, s68
	ds_read_b128 v[182:185], v141 offset:16384
	ds_read_b128 v[186:189], v141 offset:17408
	ds_read_b128 v[190:193], v141 offset:18432
	ds_read_b128 v[194:197], v141 offset:19456
	ds_read_b128 v[198:201], v141 offset:20480
	ds_read_b128 v[202:205], v141 offset:21504
	ds_read_b128 v[206:209], v141 offset:22528
	ds_read_b128 v[220:223], v141 offset:23552
	global_load_lds_dwordx4 v[146:147], off
	s_add_i32 m0, s68, 0x2000
	s_add_u32 s68, s30, 0xb0000
	v_lshl_add_u64 v[150:151], s[30:31], 0, v[130:131]
	s_addc_u32 s69, s31, 0
	s_add_i32 s65, s65, s43
	global_load_lds_dwordx4 v[150:151], off
	v_lshl_add_u64 v[210:211], s[68:69], 0, v[0:1]
	s_mov_b32 m0, s65
	v_lshl_add_u64 v[212:213], s[34:35], 0, v[130:131]
	global_load_lds_dwordx4 v[210:211], off
	v_lshl_add_u64 v[210:211], s[68:69], 0, v[130:131]
	s_add_i32 m0, s65, 0x2000
	s_nop 0
	global_load_lds_dwordx4 v[210:211], off
	v_lshl_add_u64 v[210:211], s[34:35], 0, v[0:1]
	s_mov_b32 m0, s44
	s_nop 0
	global_load_lds_dwordx4 v[210:211], off
	s_mov_b32 m0, s45
	s_nop 0
	global_load_lds_dwordx4 v[212:213], off
	s_waitcnt vmcnt(8)
	s_waitcnt lgkmcnt(0)
	s_barrier
; #define PG8_STAGE(bufoff, gbase, voff) do { _Pragma("unroll") for (int _i = 0; _i < 2; ++_i) \
;         __builtin_amdgcn_global_load_lds((const unsigned*)((const char*)(gbase) + (voff)[_i]), (PG8_LAS unsigned*)(lds + (bufoff) + ldsw + _i * 8192), 16, 0, 0); } while (0)
; #define PG8_LDA(dst, b, h) do { _Pragma("unroll") for (int m = 0; m < 4; ++m) _Pragma("unroll") for (int k = 0; k < 2; ++k) dst[m][k] = *(const PG8_LAS bf16x8*)(lds + PG8_SA(b, h) + aoff + m * 2048 + k * 1024); } while (0)
; #define PG8_LDB(dst, b, h) do { _Pragma("unroll") for (int n = 0; n < 2; ++n) _Pragma("unroll") for (int k = 0; k < 2; ++k) dst[n][k] = *(const PG8_LAS bf16x8*)(lds + PG8_SB(b, h) + boff + n * 2048 + k * 1024); } while (0)
; #define PG8_MMA(ai, bj, At, Bt) do { __builtin_amdgcn_s_setprio(1); _Pragma("unroll") for (int m = 0; m < 4; ++m) _Pragma("unroll") for (int n = 0; n < 2; ++n) _Pragma("unroll") for (int k = 0; k < 2; ++k) \
;         acc[ai][bj][m][n] = __builtin_amdgcn_mfma_f32_16x16x32_bf16(Bt[n][k], At[m][k], acc[ai][bj][m][n], 0, 0, 0); __builtin_amdgcn_s_setprio(0); } while (0)
; template <class Epi, class Sched, bool ALIGN_EPI = false, bool SP2 = false>
; __device__ __forceinline__ void gemm_phase(PG8_LAS unsigned char* lds, const Gemm g, const Sched& S, const Epi& E) {
;     ...
;             PG8_LDB(B0, 0, 0); PG8_LDB(B1, 0, 1); PG8_SCHED; PG8_LDA(At, 0, 0); PG8_STAGE(PG8_SA(1, 1), a1 + hstep, voffA);
;             PG8_WAIT_V(8); PG8_WAIT_L(0); PG8_BAR; PG8_MMA(0, 0, At, B0); PG8_MMA(0, 1, At, B1); PG8_BAR; PG8_SCHED;
;             if (full) PG8_LDA(At, 0, 1); PG8_STAGE(PG8_SB(0, 0), b2, voffB); PG8_STAGE(PG8_SB(0, 1), b2 + hstep, voffB); PG8_STAGE(PG8_SA(0, 0), a2, voffA);
;             PG8_WAIT_V(8); PG8_WAIT_L(0); PG8_BAR; if (full) { PG8_MMA(1, 0, At, B0); PG8_MMA(1, 1, At, B1); } PG8_BAR; PG8_SCHED;
;             PG8_LDB(B0, 1, 0); PG8_LDB(B1, 1, 1); PG8_SCHED; PG8_LDA(At, 1, 0); PG8_STAGE(PG8_SA(0, 1), a2 + hstep, voffA);
;             PG8_WAIT_V(8); PG8_WAIT_L(0); PG8_BAR; PG8_MMA(0, 0, At, B0); PG8_MMA(0, 1, At, B1); PG8_BAR; PG8_SCHED;
;             if (full) PG8_LDA(At, 1, 1); PG8_STAGE(PG8_SB(1, 0), b3, voffB); PG8_STAGE(PG8_SB(1, 1), b3 + hstep, voffB); PG8_STAGE(PG8_SA(1, 0), a3, voffA);
;             PG8_WAIT_V(8); PG8_WAIT_L(0); PG8_BAR; if (full) { PG8_MMA(1, 0, At, B0); PG8_MMA(1, 1, At, B1); } PG8_BAR; PG8_SCHED;
	s_setprio 1
	s_waitcnt lgkmcnt(0)
	v_mfma_f32_16x16x32_bf16 v[102:105], v[142:145], v[182:185], v[102:105]
	v_mfma_f32_16x16x32_bf16 v[98:101], v[158:161], v[182:185], v[98:101]
	v_mfma_f32_16x16x32_bf16 v[90:93], v[142:145], v[190:193], v[90:93]
	v_mfma_f32_16x16x32_bf16 v[86:89], v[158:161], v[190:193], v[86:89]
	v_mfma_f32_16x16x32_bf16 v[78:81], v[142:145], v[198:201], v[78:81]
	v_mfma_f32_16x16x32_bf16 v[74:77], v[158:161], v[198:201], v[74:77]
	v_mfma_f32_16x16x32_bf16 v[70:73], v[142:145], v[206:209], v[70:73]
	v_mfma_f32_16x16x32_bf16 v[66:69], v[158:161], v[206:209], v[66:69]
	v_mfma_f32_16x16x32_bf16 v[102:105], v[154:157], v[186:189], v[102:105]
	v_mfma_f32_16x16x32_bf16 v[98:101], v[162:165], v[186:189], v[98:101]
	v_mfma_f32_16x16x32_bf16 v[90:93], v[154:157], v[194:197], v[90:93]
	v_mfma_f32_16x16x32_bf16 v[86:89], v[162:165], v[194:197], v[86:89]
	v_mfma_f32_16x16x32_bf16 v[78:81], v[154:157], v[202:205], v[78:81]
	v_mfma_f32_16x16x32_bf16 v[74:77], v[162:165], v[202:205], v[74:77]
	v_mfma_f32_16x16x32_bf16 v[70:73], v[154:157], v[220:223], v[70:73]
	v_mfma_f32_16x16x32_bf16 v[66:69], v[162:165], v[220:223], v[66:69]
	s_setprio 0
	s_setprio 1
	v_mfma_f32_16x16x32_bf16 v[54:57], v[166:169], v[182:185], v[54:57]
	v_mfma_f32_16x16x32_bf16 v[18:21], v[174:177], v[182:185], v[18:21]
	v_mfma_f32_16x16x32_bf16 v[58:61], v[166:169], v[190:193], v[58:61]
	v_mfma_f32_16x16x32_bf16 v[30:33], v[174:177], v[190:193], v[30:33]
	v_mfma_f32_16x16x32_bf16 v[62:65], v[166:169], v[198:201], v[62:65]
	v_mfma_f32_16x16x32_bf16 v[38:41], v[174:177], v[198:201], v[38:41]
	v_mfma_f32_16x16x32_bf16 v[50:53], v[166:169], v[206:209], v[50:53]
	v_mfma_f32_16x16x32_bf16 v[22:25], v[174:177], v[206:209], v[22:25]
	v_mfma_f32_16x16x32_bf16 v[54:57], v[170:173], v[186:189], v[54:57]
	v_mfma_f32_16x16x32_bf16 v[18:21], v[178:181], v[186:189], v[18:21]
	v_mfma_f32_16x16x32_bf16 v[58:61], v[170:173], v[194:197], v[58:61]
	v_mfma_f32_16x16x32_bf16 v[30:33], v[178:181], v[194:197], v[30:33]
	v_mfma_f32_16x16x32_bf16 v[62:65], v[170:173], v[202:205], v[62:65]
	v_mfma_f32_16x16x32_bf16 v[38:41], v[178:181], v[202:205], v[38:41]
	v_mfma_f32_16x16x32_bf16 v[50:53], v[170:173], v[220:223], v[50:53]
	v_mfma_f32_16x16x32_bf16 v[22:25], v[178:181], v[220:223], v[22:25]
	s_barrier
	s_setprio 0
	s_add_i32 s65, 0, 0x18000
	v_add_u32_e32 v149, s65, v140
	s_add_i32 s68, 0, 0x1c000
	ds_read_b128 v[142:145], v149
	ds_read_b128 v[154:157], v149 offset:1024
	ds_read_b128 v[158:161], v149 offset:2048
	ds_read_b128 v[162:165], v149 offset:3072
	v_add_u32_e32 v149, s68, v140
	ds_read_b128 v[166:169], v149
	ds_read_b128 v[170:173], v149 offset:1024
	ds_read_b128 v[174:177], v149 offset:2048
	ds_read_b128 v[178:181], v149 offset:3072
	s_add_u32 s34, s34, 0xb0000
	s_addc_u32 s35, s35, 0
	s_mov_b32 m0, s48
	v_lshl_add_u64 v[214:215], s[34:35], 0, v[0:1]
	ds_read_b128 v[182:185], v141 offset:32768
	ds_read_b128 v[186:189], v141 offset:33792
	ds_read_b128 v[190:193], v141 offset:34816
	ds_read_b128 v[194:197], v141 offset:35840
	ds_read_b128 v[198:201], v141 offset:36864
	ds_read_b128 v[202:205], v141 offset:37888
	ds_read_b128 v[206:209], v141 offset:38912
	ds_read_b128 v[220:223], v141 offset:39936
	global_load_lds_dwordx4 v[214:215], off
	v_lshl_add_u64 v[214:215], s[34:35], 0, v[130:131]
	s_mov_b32 m0, s54
	s_nop 0
	global_load_lds_dwordx4 v[214:215], off
	s_waitcnt vmcnt(8)
	s_waitcnt lgkmcnt(0)
	s_barrier
	s_setprio 1
	s_waitcnt lgkmcnt(0)
	v_mfma_f32_16x16x32_bf16 v[114:117], v[142:145], v[182:185], v[114:117]
	v_mfma_f32_16x16x32_bf16 v[82:85], v[158:161], v[182:185], v[82:85]
	v_mfma_f32_16x16x32_bf16 v[122:125], v[142:145], v[190:193], v[122:125]
	v_mfma_f32_16x16x32_bf16 v[94:97], v[158:161], v[190:193], v[94:97]
	v_mfma_f32_16x16x32_bf16 v[126:129], v[142:145], v[198:201], v[126:129]
	v_mfma_f32_16x16x32_bf16 v[106:109], v[158:161], v[198:201], v[106:109]
	v_mfma_f32_16x16x32_bf16 v[118:121], v[142:145], v[206:209], v[118:121]
	v_mfma_f32_16x16x32_bf16 v[110:113], v[158:161], v[206:209], v[110:113]
	v_mfma_f32_16x16x32_bf16 v[114:117], v[154:157], v[186:189], v[114:117]
	v_mfma_f32_16x16x32_bf16 v[82:85], v[162:165], v[186:189], v[82:85]
	v_mfma_f32_16x16x32_bf16 v[122:125], v[154:157], v[194:197], v[122:125]
	v_mfma_f32_16x16x32_bf16 v[94:97], v[162:165], v[194:197], v[94:97]
	v_mfma_f32_16x16x32_bf16 v[126:129], v[154:157], v[202:205], v[126:129]
	v_mfma_f32_16x16x32_bf16 v[106:109], v[162:165], v[202:205], v[106:109]
	v_mfma_f32_16x16x32_bf16 v[118:121], v[154:157], v[220:223], v[118:121]
	v_mfma_f32_16x16x32_bf16 v[110:113], v[162:165], v[220:223], v[110:113]
	s_setprio 0
	s_setprio 1
	v_mfma_f32_16x16x32_bf16 v[26:29], v[166:169], v[182:185], v[26:29]
	v_mfma_f32_16x16x32_bf16 v[2:5], v[174:177], v[182:185], v[2:5]
	v_mfma_f32_16x16x32_bf16 v[34:37], v[166:169], v[190:193], v[34:37]
	v_mfma_f32_16x16x32_bf16 v[6:9], v[174:177], v[190:193], v[6:9]
	v_mfma_f32_16x16x32_bf16 v[42:45], v[166:169], v[198:201], v[42:45]
	v_mfma_f32_16x16x32_bf16 v[10:13], v[174:177], v[198:201], v[10:13]
	v_mfma_f32_16x16x32_bf16 v[46:49], v[166:169], v[206:209], v[46:49]
	v_mfma_f32_16x16x32_bf16 v[14:17], v[174:177], v[206:209], v[14:17]
	v_mfma_f32_16x16x32_bf16 v[26:29], v[170:173], v[186:189], v[26:29]
	v_mfma_f32_16x16x32_bf16 v[2:5], v[178:181], v[186:189], v[2:5]
	v_mfma_f32_16x16x32_bf16 v[34:37], v[170:173], v[194:197], v[34:37]
	v_mfma_f32_16x16x32_bf16 v[6:9], v[178:181], v[194:197], v[6:9]
	v_mfma_f32_16x16x32_bf16 v[42:45], v[170:173], v[202:205], v[42:45]
	v_mfma_f32_16x16x32_bf16 v[10:13], v[178:181], v[202:205], v[10:13]
	v_mfma_f32_16x16x32_bf16 v[46:49], v[170:173], v[220:223], v[46:49]
	v_mfma_f32_16x16x32_bf16 v[14:17], v[178:181], v[220:223], v[14:17]
	s_barrier
; #define PG8_STAGE(bufoff, gbase, voff) do { _Pragma("unroll") for (int _i = 0; _i < 2; ++_i) \
;         __builtin_amdgcn_global_load_lds((const unsigned*)((const char*)(gbase) + (voff)[_i]), (PG8_LAS unsigned*)(lds + (bufoff) + ldsw + _i * 8192), 16, 0, 0); } while (0)
; #define PG8_LDA(dst, b, h) do { _Pragma("unroll") for (int m = 0; m < 4; ++m) _Pragma("unroll") for (int k = 0; k < 2; ++k) dst[m][k] = *(const PG8_LAS bf16x8*)(lds + PG8_SA(b, h) + aoff + m * 2048 + k * 1024); } while (0)
; #define PG8_LDB(dst, b, h) do { _Pragma("unroll") for (int n = 0; n < 2; ++n) _Pragma("unroll") for (int k = 0; k < 2; ++k) dst[n][k] = *(const PG8_LAS bf16x8*)(lds + PG8_SB(b, h) + boff + n * 2048 + k * 1024); } while (0)
; template <class Epi, class Sched, bool ALIGN_EPI = false, bool SP2 = false>
; __device__ __forceinline__ void gemm_phase(PG8_LAS unsigned char* lds, const Gemm g, const Sched& S, const Epi& E) {
;     ...
;             PG8_LDB(B0, 0, 0); PG8_LDB(B1, 0, 1); PG8_SCHED; PG8_LDA(At, 0, 0); PG8_STAGE(PG8_SA(1, 1), a1 + hstep, voffA);
;             PG8_WAIT_V(8); PG8_WAIT_L(0); PG8_BAR; PG8_MMA(0, 0, At, B0); PG8_MMA(0, 1, At, B1); PG8_BAR; PG8_SCHED;
;             if (full) PG8_LDA(At, 0, 1); PG8_STAGE(PG8_SB(0, 0), b2, voffB); PG8_STAGE(PG8_SB(0, 1), b2 + hstep, voffB); PG8_STAGE(PG8_SA(0, 0), a2, voffA);
;             PG8_WAIT_V(8); PG8_WAIT_L(0); PG8_BAR; if (full) { PG8_MMA(1, 0, At, B0); PG8_MMA(1, 1, At, B1); } PG8_BAR; PG8_SCHED;
;             PG8_LDB(B0, 1, 0); PG8_LDB(B1, 1, 1); PG8_SCHED; PG8_LDA(At, 1, 0); PG8_STAGE(PG8_SA(0, 1), a2 + hstep, voffA);
;             PG8_WAIT_V(8); PG8_WAIT_L(0); PG8_BAR; PG8_MMA(0, 0, At, B0); PG8_MMA(0, 1, At, B1); PG8_BAR; PG8_SCHED;
;             if (full) PG8_LDA(At, 1, 1); PG8_STAGE(PG8_SB(1, 0), b3, voffB); PG8_STAGE(PG8_SB(1, 1), b3 + hstep, voffB); PG8_STAGE(PG8_SA(1, 0), a3, voffA);
;             PG8_WAIT_V(8); PG8_WAIT_L(0); PG8_BAR; if (full) { PG8_MMA(1, 0, At, B0); PG8_MMA(1, 1, At, B1); } PG8_BAR; PG8_SCHED;
;     ...
;         if (!Sched::KEEP || (nxt.pn >> 2) == 0) {
; #pragma unroll
;         for (int a = 0; a < 2; ++a)
; #pragma unroll
;             for (int b = 0; b < 2; ++b)
; #pragma unroll
;                 for (int m = 0; m < 4; ++m)
; #pragma unroll
;                     for (int n = 0; n < 2; ++n) acc[a][b][m][n] = (f32x4){0.f, 0.f, 0.f, 0.f};
;         }
;         cur = nxt; cA = nA; cB = nB; ++ui;
	s_setprio 0
	s_add_i32 s34, s65, s43
	v_lshl_add_u64 v[146:147], v[146:147], 0, s[52:53]
	s_mov_b32 m0, s34
	ds_read_b128 v[182:185], v141 offset:49152
	ds_read_b128 v[186:189], v141 offset:50176
	ds_read_b128 v[190:193], v141 offset:51200
	ds_read_b128 v[194:197], v141 offset:52224
	ds_read_b128 v[198:201], v141 offset:53248
	ds_read_b128 v[202:205], v141 offset:54272
	ds_read_b128 v[206:209], v141 offset:55296
	ds_read_b128 v[220:223], v141 offset:56320
	global_load_lds_dwordx4 v[146:147], off
	s_add_i32 m0, s34, 0x2000
	s_add_u32 s30, s30, 0xb0080
	v_lshl_add_u64 v[146:147], v[150:151], 0, s[52:53]
	s_addc_u32 s31, s31, 0
	s_add_i32 s34, s68, s43
	global_load_lds_dwordx4 v[146:147], off
	v_lshl_add_u64 v[146:147], s[30:31], 0, v[0:1]
	s_mov_b32 m0, s34
	s_nop 0
	global_load_lds_dwordx4 v[146:147], off
	v_lshl_add_u64 v[146:147], s[30:31], 0, v[130:131]
	s_add_i32 m0, s34, 0x2000
	s_nop 0
	global_load_lds_dwordx4 v[146:147], off
	v_lshl_add_u64 v[146:147], v[210:211], 0, s[52:53]
	s_mov_b32 m0, s55
	s_nop 0
	global_load_lds_dwordx4 v[146:147], off
	v_lshl_add_u64 v[146:147], v[212:213], 0, s[52:53]
	s_mov_b32 m0, s56
	s_nop 0
	global_load_lds_dwordx4 v[146:147], off
	s_waitcnt vmcnt(8)
	s_waitcnt lgkmcnt(0)
	s_barrier
	s_setprio 1
	s_waitcnt lgkmcnt(0)
	v_mfma_f32_16x16x32_bf16 v[102:105], v[142:145], v[182:185], v[102:105]
	v_mfma_f32_16x16x32_bf16 v[98:101], v[158:161], v[182:185], v[98:101]
	v_mfma_f32_16x16x32_bf16 v[90:93], v[142:145], v[190:193], v[90:93]
	v_mfma_f32_16x16x32_bf16 v[86:89], v[158:161], v[190:193], v[86:89]
	v_mfma_f32_16x16x32_bf16 v[78:81], v[142:145], v[198:201], v[78:81]
	v_mfma_f32_16x16x32_bf16 v[74:77], v[158:161], v[198:201], v[74:77]
	v_mfma_f32_16x16x32_bf16 v[70:73], v[142:145], v[206:209], v[70:73]
	v_mfma_f32_16x16x32_bf16 v[66:69], v[158:161], v[206:209], v[66:69]
	v_mfma_f32_16x16x32_bf16 v[102:105], v[154:157], v[186:189], v[102:105]
	v_mfma_f32_16x16x32_bf16 v[98:101], v[162:165], v[186:189], v[98:101]
	v_mfma_f32_16x16x32_bf16 v[90:93], v[154:157], v[194:197], v[90:93]
	v_mfma_f32_16x16x32_bf16 v[86:89], v[162:165], v[194:197], v[86:89]
	v_mfma_f32_16x16x32_bf16 v[78:81], v[154:157], v[202:205], v[78:81]
	v_mfma_f32_16x16x32_bf16 v[74:77], v[162:165], v[202:205], v[74:77]
	v_mfma_f32_16x16x32_bf16 v[70:73], v[154:157], v[220:223], v[70:73]
	v_mfma_f32_16x16x32_bf16 v[66:69], v[162:165], v[220:223], v[66:69]
	s_setprio 0
	s_setprio 1
	v_mfma_f32_16x16x32_bf16 v[54:57], v[166:169], v[182:185], v[54:57]
	v_mfma_f32_16x16x32_bf16 v[18:21], v[174:177], v[182:185], v[18:21]
	v_mfma_f32_16x16x32_bf16 v[58:61], v[166:169], v[190:193], v[58:61]
	v_mfma_f32_16x16x32_bf16 v[30:33], v[174:177], v[190:193], v[30:33]
	v_mfma_f32_16x16x32_bf16 v[62:65], v[166:169], v[198:201], v[62:65]
	v_mfma_f32_16x16x32_bf16 v[38:41], v[174:177], v[198:201], v[38:41]
	v_mfma_f32_16x16x32_bf16 v[50:53], v[166:169], v[206:209], v[50:53]
	v_mfma_f32_16x16x32_bf16 v[22:25], v[174:177], v[206:209], v[22:25]
	v_mfma_f32_16x16x32_bf16 v[54:57], v[170:173], v[186:189], v[54:57]
	v_mfma_f32_16x16x32_bf16 v[18:21], v[178:181], v[186:189], v[18:21]
	v_mfma_f32_16x16x32_bf16 v[58:61], v[170:173], v[194:197], v[58:61]
	v_mfma_f32_16x16x32_bf16 v[30:33], v[178:181], v[194:197], v[30:33]
	v_mfma_f32_16x16x32_bf16 v[62:65], v[170:173], v[202:205], v[62:65]
	v_mfma_f32_16x16x32_bf16 v[38:41], v[178:181], v[202:205], v[38:41]
	v_mfma_f32_16x16x32_bf16 v[50:53], v[170:173], v[220:223], v[50:53]
	v_mfma_f32_16x16x32_bf16 v[22:25], v[178:181], v[220:223], v[22:25]
	s_barrier
	s_setprio 0
	s_add_i32 s64, s64, 2
	s_add_u32 s28, s28, 0x100
	s_addc_u32 s29, s29, 0
	s_cmp_gt_u32 s64, 41
	s_cbranch_scc0 .LBB0_382
	s_add_u32 s28, s62, 0xffffff00
	s_addc_u32 s29, s63, -1
	s_and_b64 vcc, exec, s[6:7]
	s_cbranch_vccnz .LBB0_369
	v_mov_b32_e32 v22, 0
	s_mov_b32 s18, s59
	s_mov_b32 s37, s60
	s_mov_b64 s[24:25], s[26:27]
	s_mov_b32 s58, s61
	v_mov_b32_e32 v23, v22
	v_mov_b32_e32 v24, v22
	v_mov_b32_e32 v25, v22
	v_mov_b32_e32 v50, v22
	v_mov_b32_e32 v51, v22
	v_mov_b32_e32 v52, v22
	v_mov_b32_e32 v53, v22
	v_mov_b32_e32 v38, v22
	v_mov_b32_e32 v39, v22
	v_mov_b32_e32 v40, v22
	v_mov_b32_e32 v41, v22
	v_mov_b32_e32 v62, v22
	v_mov_b32_e32 v63, v22
	v_mov_b32_e32 v64, v22
	v_mov_b32_e32 v65, v22
	v_mov_b32_e32 v30, v22
	v_mov_b32_e32 v31, v22
	v_mov_b32_e32 v32, v22
	v_mov_b32_e32 v33, v22
	v_mov_b32_e32 v58, v22
	v_mov_b32_e32 v59, v22
	v_mov_b32_e32 v60, v22
	v_mov_b32_e32 v61, v22
	v_mov_b32_e32 v18, v22
	v_mov_b32_e32 v19, v22
	v_mov_b32_e32 v20, v22
	v_mov_b32_e32 v21, v22
	v_mov_b32_e32 v54, v22
	v_mov_b32_e32 v55, v22
	v_mov_b32_e32 v56, v22
	v_mov_b32_e32 v57, v22
	v_mov_b32_e32 v66, v22
	v_mov_b32_e32 v67, v22
	v_mov_b32_e32 v68, v22
	v_mov_b32_e32 v69, v22
	v_mov_b32_e32 v70, v22
	v_mov_b32_e32 v71, v22
	v_mov_b32_e32 v72, v22
	v_mov_b32_e32 v73, v22
	v_mov_b32_e32 v74, v22
	v_mov_b32_e32 v75, v22
	v_mov_b32_e32 v76, v22
	v_mov_b32_e32 v77, v22
	v_mov_b32_e32 v78, v22
	v_mov_b32_e32 v79, v22
	v_mov_b32_e32 v80, v22
	v_mov_b32_e32 v81, v22
	v_mov_b32_e32 v86, v22
	v_mov_b32_e32 v87, v22
	v_mov_b32_e32 v88, v22
	v_mov_b32_e32 v89, v22
	v_mov_b32_e32 v90, v22
	v_mov_b32_e32 v91, v22
	v_mov_b32_e32 v92, v22
	v_mov_b32_e32 v93, v22
	v_mov_b32_e32 v98, v22
	v_mov_b32_e32 v99, v22
	v_mov_b32_e32 v100, v22
	v_mov_b32_e32 v101, v22
	v_mov_b32_e32 v102, v22
	v_mov_b32_e32 v103, v22
	v_mov_b32_e32 v104, v22
	v_mov_b32_e32 v105, v22
	v_mov_b32_e32 v14, v22
	v_mov_b32_e32 v15, v22
	v_mov_b32_e32 v16, v22
	v_mov_b32_e32 v17, v22
	v_mov_b32_e32 v46, v22
	v_mov_b32_e32 v47, v22
	v_mov_b32_e32 v48, v22
	v_mov_b32_e32 v49, v22
	v_mov_b32_e32 v10, v22
	v_mov_b32_e32 v11, v22
	v_mov_b32_e32 v12, v22
	v_mov_b32_e32 v13, v22
	v_mov_b32_e32 v42, v22
	v_mov_b32_e32 v43, v22
	v_mov_b32_e32 v44, v22
	v_mov_b32_e32 v45, v22
	v_mov_b32_e32 v6, v22
	v_mov_b32_e32 v7, v22
	v_mov_b32_e32 v8, v22
	v_mov_b32_e32 v9, v22
	v_mov_b32_e32 v34, v22
	v_mov_b32_e32 v35, v22
	v_mov_b32_e32 v36, v22
	v_mov_b32_e32 v37, v22
	v_mov_b32_e32 v2, v22
	v_mov_b32_e32 v3, v22
	v_mov_b32_e32 v4, v22
	v_mov_b32_e32 v5, v22
	v_mov_b32_e32 v26, v22
	v_mov_b32_e32 v27, v22
	v_mov_b32_e32 v28, v22
	v_mov_b32_e32 v29, v22
	v_mov_b32_e32 v110, v22
	v_mov_b32_e32 v111, v22
	v_mov_b32_e32 v112, v22
	v_mov_b32_e32 v113, v22
	v_mov_b32_e32 v118, v22
	v_mov_b32_e32 v119, v22
	v_mov_b32_e32 v120, v22
	v_mov_b32_e32 v121, v22
	v_mov_b32_e32 v106, v22
	v_mov_b32_e32 v107, v22
	v_mov_b32_e32 v108, v22
	v_mov_b32_e32 v109, v22
	v_mov_b32_e32 v126, v22
	v_mov_b32_e32 v127, v22
	v_mov_b32_e32 v128, v22
	v_mov_b32_e32 v129, v22
	v_mov_b32_e32 v94, v22
	v_mov_b32_e32 v95, v22
	v_mov_b32_e32 v96, v22
	v_mov_b32_e32 v97, v22
	v_mov_b32_e32 v122, v22
	v_mov_b32_e32 v123, v22
	v_mov_b32_e32 v124, v22
	v_mov_b32_e32 v125, v22
	v_mov_b32_e32 v82, v22
	v_mov_b32_e32 v83, v22
	v_mov_b32_e32 v84, v22
	v_mov_b32_e32 v85, v22
	v_mov_b32_e32 v114, v22
	v_mov_b32_e32 v115, v22
	v_mov_b32_e32 v116, v22
	v_mov_b32_e32 v117, v22
	s_andn2_b64 vcc, exec, s[4:5]
	s_cbranch_vccnz .LBB0_370

; #define PG8_STAGE(bufoff, gbase, voff) do { _Pragma("unroll") for (int _i = 0; _i < 2; ++_i) \
;         __builtin_amdgcn_global_load_lds((const unsigned*)((const char*)(gbase) + (voff)[_i]), (PG8_LAS unsigned*)(lds + (bufoff) + ldsw + _i * 8192), 16, 0, 0); } while (0)
; #define PG8_LDA(dst, b, h) do { _Pragma("unroll") for (int m = 0; m < 4; ++m) _Pragma("unroll") for (int k = 0; k < 2; ++k) dst[m][k] = *(const PG8_LAS bf16x8*)(lds + PG8_SA(b, h) + aoff + m * 2048 + k * 1024); } while (0)
; #define PG8_LDB(dst, b, h) do { _Pragma("unroll") for (int n = 0; n < 2; ++n) _Pragma("unroll") for (int k = 0; k < 2; ++k) dst[n][k] = *(const PG8_LAS bf16x8*)(lds + PG8_SB(b, h) + boff + n * 2048 + k * 1024); } while (0)
; #define PG8_MMA(ai, bj, At, Bt) do { __builtin_amdgcn_s_setprio(1); _Pragma("unroll") for (int m = 0; m < 4; ++m) _Pragma("unroll") for (int n = 0; n < 2; ++n) _Pragma("unroll") for (int k = 0; k < 2; ++k) \
;         acc[ai][bj][m][n] = __builtin_amdgcn_mfma_f32_16x16x32_bf16(Bt[n][k], At[m][k], acc[ai][bj][m][n], 0, 0, 0); __builtin_amdgcn_s_setprio(0); } while (0)
; template <class Epi, class Sched, bool ALIGN_EPI = false, bool SP2 = false>
; __device__ __forceinline__ void gemm_phase(PG8_LAS unsigned char* lds, const Gemm g, const Sched& S, const Epi& E) {
;     ...
;             PG8_LDB(B0, 0, 0); PG8_LDB(B1, 0, 1); PG8_SCHED; PG8_LDA(At, 0, 0); PG8_STAGE(PG8_SA(1, 1), a1 + hstep, voffA);
;             PG8_WAIT_V(8); PG8_WAIT_L(0); PG8_BAR; PG8_MMA(0, 0, At, B0); PG8_MMA(0, 1, At, B1); PG8_BAR; PG8_SCHED;
;             if (full) PG8_LDA(At, 0, 1); PG8_STAGE(PG8_SB(0, 0), b2, voffB); PG8_STAGE(PG8_SB(0, 1), b2 + hstep, voffB); PG8_STAGE(PG8_SA(0, 0), a2, voffA);
;             PG8_WAIT_V(8); PG8_WAIT_L(0); PG8_BAR; if (full) { PG8_MMA(1, 0, At, B0); PG8_MMA(1, 1, At, B1); } PG8_BAR; PG8_SCHED;
;             PG8_LDB(B0, 1, 0); PG8_LDB(B1, 1, 1); PG8_SCHED; PG8_LDA(At, 1, 0); PG8_STAGE(PG8_SA(0, 1), a2 + hstep, voffA);
;             PG8_WAIT_V(8); PG8_WAIT_L(0); PG8_BAR; PG8_MMA(0, 0, At, B0); PG8_MMA(0, 1, At, B1); PG8_BAR; PG8_SCHED;
;             if (full) PG8_LDA(At, 1, 1); PG8_STAGE(PG8_SB(1, 0), b3, voffB); PG8_STAGE(PG8_SB(1, 1), b3 + hstep, voffB); PG8_STAGE(PG8_SA(1, 0), a3, voffA);
;             PG8_WAIT_V(8); PG8_WAIT_L(0); PG8_BAR; if (full) { PG8_MMA(1, 0, At, B0); PG8_MMA(1, 1, At, B1); } PG8_BAR; PG8_SCHED;
.LBB0_520:
	s_barrier
	s_setprio 0
	s_add_i32 s82, s82, 2
	s_add_u32 s34, s34, 0x100
	s_addc_u32 s35, s35, 0
	s_add_u32 s80, s80, 0x100
	s_addc_u32 s81, s81, 0
	s_cmp_gt_u32 s82, 13
	s_cbranch_scc1 .LBB0_529
.LBB0_521:
	v_add_u32_e32 v0, 0x10000, v225
	ds_read_b128 v[148:151], v0
	ds_read_b128 v[152:155], v0 offset:1024
	ds_read_b128 v[156:159], v0 offset:2048
	ds_read_b128 v[160:163], v0 offset:3072
	v_add_u32_e32 v0, 0x14000, v225
	ds_read_b128 v[132:135], v0
	ds_read_b128 v[136:139], v0 offset:1024
	ds_read_b128 v[140:143], v0 offset:2048
	ds_read_b128 v[144:147], v0 offset:3072
	v_lshl_add_u64 v[2:3], s[34:35], 0, v[204:205]
	s_add_i32 m0, s27, 0xc000
	ds_read_b128 v[176:179], v241
	ds_read_b128 v[192:195], v241 offset:1024
	ds_read_b128 v[172:175], v241 offset:2048
	ds_read_b128 v[188:191], v241 offset:3072
	ds_read_b128 v[168:171], v241 offset:4096
	ds_read_b128 v[184:187], v241 offset:5120
	ds_read_b128 v[164:167], v241 offset:6144
	ds_read_b128 v[180:183], v241 offset:7168
	global_load_lds_dwordx4 v[2:3], off
	v_lshl_add_u64 v[2:3], s[34:35], 0, v[206:207]
	s_add_i32 m0, s27, 0xe000
	s_nop 0
	global_load_lds_dwordx4 v[2:3], off
	s_waitcnt vmcnt(8)
	s_waitcnt lgkmcnt(0)
	s_barrier
	s_setprio 1
	s_waitcnt lgkmcnt(0)
	v_mfma_f32_16x16x32_bf16 v[128:131], v[148:151], v[176:179], v[128:131]
	v_mfma_f32_16x16x32_bf16 v[124:127], v[156:159], v[176:179], v[124:127]
	v_mfma_f32_16x16x32_bf16 v[112:115], v[148:151], v[172:175], v[112:115]
	v_mfma_f32_16x16x32_bf16 v[108:111], v[156:159], v[172:175], v[108:111]
	v_mfma_f32_16x16x32_bf16 v[96:99], v[148:151], v[168:171], v[96:99]
	v_mfma_f32_16x16x32_bf16 v[92:95], v[156:159], v[168:171], v[92:95]
	v_mfma_f32_16x16x32_bf16 v[80:83], v[148:151], v[164:167], v[80:83]
	v_mfma_f32_16x16x32_bf16 v[76:79], v[156:159], v[164:167], v[76:79]
	v_mfma_f32_16x16x32_bf16 v[128:131], v[152:155], v[192:195], v[128:131]
	v_mfma_f32_16x16x32_bf16 v[124:127], v[160:163], v[192:195], v[124:127]
	v_mfma_f32_16x16x32_bf16 v[112:115], v[152:155], v[188:191], v[112:115]
	v_mfma_f32_16x16x32_bf16 v[108:111], v[160:163], v[188:191], v[108:111]
	v_mfma_f32_16x16x32_bf16 v[96:99], v[152:155], v[184:187], v[96:99]
	v_mfma_f32_16x16x32_bf16 v[92:95], v[160:163], v[184:187], v[92:95]
	v_mfma_f32_16x16x32_bf16 v[80:83], v[152:155], v[180:183], v[80:83]
	v_mfma_f32_16x16x32_bf16 v[76:79], v[160:163], v[180:183], v[76:79]
	s_setprio 0
	s_setprio 1
	v_mfma_f32_16x16x32_bf16 v[120:123], v[132:135], v[176:179], v[120:123]
	v_mfma_f32_16x16x32_bf16 v[116:119], v[140:143], v[176:179], v[116:119]
	v_mfma_f32_16x16x32_bf16 v[104:107], v[132:135], v[172:175], v[104:107]
	v_mfma_f32_16x16x32_bf16 v[100:103], v[140:143], v[172:175], v[100:103]
	v_mfma_f32_16x16x32_bf16 v[88:91], v[132:135], v[168:171], v[88:91]
	v_mfma_f32_16x16x32_bf16 v[84:87], v[140:143], v[168:171], v[84:87]
	v_mfma_f32_16x16x32_bf16 v[72:75], v[132:135], v[164:167], v[72:75]
	v_mfma_f32_16x16x32_bf16 v[68:71], v[140:143], v[164:167], v[68:71]
	v_mfma_f32_16x16x32_bf16 v[120:123], v[136:139], v[192:195], v[120:123]
	v_mfma_f32_16x16x32_bf16 v[116:119], v[144:147], v[192:195], v[116:119]
	v_mfma_f32_16x16x32_bf16 v[104:107], v[136:139], v[188:191], v[104:107]
	v_mfma_f32_16x16x32_bf16 v[100:103], v[144:147], v[188:191], v[100:103]
	v_mfma_f32_16x16x32_bf16 v[88:91], v[136:139], v[184:187], v[88:91]
	v_mfma_f32_16x16x32_bf16 v[84:87], v[144:147], v[184:187], v[84:87]
	v_mfma_f32_16x16x32_bf16 v[72:75], v[136:139], v[180:183], v[72:75]
	v_mfma_f32_16x16x32_bf16 v[68:71], v[144:147], v[180:183], v[68:71]
	s_barrier
	s_setprio 0
	v_cndmask_b32_e64 v0, 0, 1, s[30:31]
	v_cmp_ne_u32_e64 s[4:5], 1, v0
	s_andn2_b64 vcc, exec, s[30:31]
	s_cbranch_vccnz .LBB0_523
	ds_read_b128 v[176:179], v241 offset:16384
	ds_read_b128 v[192:195], v241 offset:17408
	ds_read_b128 v[172:175], v241 offset:18432
	ds_read_b128 v[188:191], v241 offset:19456
	ds_read_b128 v[168:171], v241 offset:20480
	ds_read_b128 v[184:187], v241 offset:21504
	ds_read_b128 v[164:167], v241 offset:22528
	ds_read_b128 v[180:183], v241 offset:23552

; #define PG8_STAGE(bufoff, gbase, voff) do { _Pragma("unroll") for (int _i = 0; _i < 2; ++_i) \
;         __builtin_amdgcn_global_load_lds((const unsigned*)((const char*)(gbase) + (voff)[_i]), (PG8_LAS unsigned*)(lds + (bufoff) + ldsw + _i * 8192), 16, 0, 0); } while (0)
; #define PG8_LDA(dst, b, h) do { _Pragma("unroll") for (int m = 0; m < 4; ++m) _Pragma("unroll") for (int k = 0; k < 2; ++k) dst[m][k] = *(const PG8_LAS bf16x8*)(lds + PG8_SA(b, h) + aoff + m * 2048 + k * 1024); } while (0)
; #define PG8_LDB(dst, b, h) do { _Pragma("unroll") for (int n = 0; n < 2; ++n) _Pragma("unroll") for (int k = 0; k < 2; ++k) dst[n][k] = *(const PG8_LAS bf16x8*)(lds + PG8_SB(b, h) + boff + n * 2048 + k * 1024); } while (0)
; #define PG8_MMA(ai, bj, At, Bt) do { __builtin_amdgcn_s_setprio(1); _Pragma("unroll") for (int m = 0; m < 4; ++m) _Pragma("unroll") for (int n = 0; n < 2; ++n) _Pragma("unroll") for (int k = 0; k < 2; ++k) \
;         acc[ai][bj][m][n] = __builtin_amdgcn_mfma_f32_16x16x32_bf16(Bt[n][k], At[m][k], acc[ai][bj][m][n], 0, 0, 0); __builtin_amdgcn_s_setprio(0); } while (0)
; #define PG8_WAIT_V(n) asm volatile("s_waitcnt vmcnt(" #n ")" ::: "memory")
; #define PG8_WAIT_L(n) asm volatile("s_waitcnt lgkmcnt(" #n ")" ::: "memory")
; #define PG8_BAR __builtin_amdgcn_s_barrier()
; #define PG8_SCHED __builtin_amdgcn_sched_barrier(0)
; template <class Epi, class Sched, bool ALIGN_EPI = false, bool SP2 = false>
; __device__ __forceinline__ void gemm_phase(PG8_LAS unsigned char* lds, const Gemm g, const Sched& S, const Epi& E) {
;     ...
;             PG8_WAIT_V(8); PG8_WAIT_L(0); PG8_BAR; if (full) { PG8_MMA(1, 0, At, B0); PG8_MMA(1, 1, At, B1); } PG8_BAR; PG8_SCHED;
;             PG8_LDB(B0, 1, 0); PG8_LDB(B1, 1, 1); PG8_SCHED; PG8_LDA(At, 1, 0); PG8_STAGE(PG8_SA(0, 1), a2 + hstep, voffA);
;             PG8_WAIT_V(8); PG8_WAIT_L(0); PG8_BAR; PG8_MMA(0, 0, At, B0); PG8_MMA(0, 1, At, B1); PG8_BAR; PG8_SCHED;
;             if (full) PG8_LDA(At, 1, 1); PG8_STAGE(PG8_SB(1, 0), b3, voffB); PG8_STAGE(PG8_SB(1, 1), b3 + hstep, voffB); PG8_STAGE(PG8_SA(1, 0), a3, voffA);
;             PG8_WAIT_V(8); PG8_WAIT_L(0); PG8_BAR; if (full) { PG8_MMA(1, 0, At, B0); PG8_MMA(1, 1, At, B1); } PG8_BAR; PG8_SCHED;
.LBB0_525:
	s_barrier
	s_setprio 0
	v_add_u32_e32 v0, 0x18000, v225
	ds_read_b128 v[148:151], v0
	ds_read_b128 v[152:155], v0 offset:1024
	ds_read_b128 v[156:159], v0 offset:2048
	ds_read_b128 v[160:163], v0 offset:3072
	v_add_u32_e32 v0, 0x1c000, v225
	ds_read_b128 v[132:135], v0
	ds_read_b128 v[136:139], v0 offset:1024
	ds_read_b128 v[140:143], v0 offset:2048
	ds_read_b128 v[144:147], v0 offset:3072
	s_add_u32 s38, s38, 0x40000
	s_addc_u32 s39, s39, 0
	s_mov_b32 m0, s58
	v_lshl_add_u64 v[212:213], s[38:39], 0, v[196:197]
	ds_read_b128 v[176:179], v241 offset:32768
	ds_read_b128 v[192:195], v241 offset:33792
	ds_read_b128 v[172:175], v241 offset:34816
	ds_read_b128 v[188:191], v241 offset:35840
	ds_read_b128 v[168:171], v241 offset:36864
	ds_read_b128 v[184:187], v241 offset:37888
	ds_read_b128 v[164:167], v241 offset:38912
	ds_read_b128 v[180:183], v241 offset:39936
	global_load_lds_dwordx4 v[212:213], off
	v_lshl_add_u64 v[212:213], s[38:39], 0, v[200:201]
	s_mov_b32 m0, s59
	s_nop 0
	global_load_lds_dwordx4 v[212:213], off
	s_waitcnt vmcnt(8)
	s_waitcnt lgkmcnt(0)
	s_barrier
	s_setprio 1
	s_waitcnt lgkmcnt(0)
	v_mfma_f32_16x16x32_bf16 v[128:131], v[148:151], v[176:179], v[128:131]
	v_mfma_f32_16x16x32_bf16 v[124:127], v[156:159], v[176:179], v[124:127]
	v_mfma_f32_16x16x32_bf16 v[112:115], v[148:151], v[172:175], v[112:115]
	v_mfma_f32_16x16x32_bf16 v[108:111], v[156:159], v[172:175], v[108:111]
	v_mfma_f32_16x16x32_bf16 v[96:99], v[148:151], v[168:171], v[96:99]
	v_mfma_f32_16x16x32_bf16 v[92:95], v[156:159], v[168:171], v[92:95]
	v_mfma_f32_16x16x32_bf16 v[80:83], v[148:151], v[164:167], v[80:83]
	v_mfma_f32_16x16x32_bf16 v[76:79], v[156:159], v[164:167], v[76:79]
	v_mfma_f32_16x16x32_bf16 v[128:131], v[152:155], v[192:195], v[128:131]
	v_mfma_f32_16x16x32_bf16 v[124:127], v[160:163], v[192:195], v[124:127]
	v_mfma_f32_16x16x32_bf16 v[112:115], v[152:155], v[188:191], v[112:115]
	v_mfma_f32_16x16x32_bf16 v[108:111], v[160:163], v[188:191], v[108:111]
	v_mfma_f32_16x16x32_bf16 v[96:99], v[152:155], v[184:187], v[96:99]
	v_mfma_f32_16x16x32_bf16 v[92:95], v[160:163], v[184:187], v[92:95]
	v_mfma_f32_16x16x32_bf16 v[80:83], v[152:155], v[180:183], v[80:83]
	v_mfma_f32_16x16x32_bf16 v[76:79], v[160:163], v[180:183], v[76:79]
	s_setprio 0
	s_setprio 1
	v_mfma_f32_16x16x32_bf16 v[120:123], v[132:135], v[176:179], v[120:123]
	v_mfma_f32_16x16x32_bf16 v[116:119], v[140:143], v[176:179], v[116:119]
	v_mfma_f32_16x16x32_bf16 v[104:107], v[132:135], v[172:175], v[104:107]
	v_mfma_f32_16x16x32_bf16 v[100:103], v[140:143], v[172:175], v[100:103]
	v_mfma_f32_16x16x32_bf16 v[88:91], v[132:135], v[168:171], v[88:91]
	v_mfma_f32_16x16x32_bf16 v[84:87], v[140:143], v[168:171], v[84:87]
	v_mfma_f32_16x16x32_bf16 v[72:75], v[132:135], v[164:167], v[72:75]
	v_mfma_f32_16x16x32_bf16 v[68:71], v[140:143], v[164:167], v[68:71]
	v_mfma_f32_16x16x32_bf16 v[120:123], v[136:139], v[192:195], v[120:123]
	v_mfma_f32_16x16x32_bf16 v[116:119], v[144:147], v[192:195], v[116:119]
	v_mfma_f32_16x16x32_bf16 v[104:107], v[136:139], v[188:191], v[104:107]
	v_mfma_f32_16x16x32_bf16 v[100:103], v[144:147], v[188:191], v[100:103]
	v_mfma_f32_16x16x32_bf16 v[88:91], v[136:139], v[184:187], v[88:91]
	v_mfma_f32_16x16x32_bf16 v[84:87], v[144:147], v[184:187], v[84:87]
	v_mfma_f32_16x16x32_bf16 v[72:75], v[136:139], v[180:183], v[72:75]
	v_mfma_f32_16x16x32_bf16 v[68:71], v[144:147], v[180:183], v[68:71]
	s_barrier
	s_setprio 0
	s_and_b64 vcc, exec, s[4:5]
	s_cbranch_vccnz .LBB0_527
	ds_read_b128 v[176:179], v241 offset:49152
	ds_read_b128 v[192:195], v241 offset:50176
	ds_read_b128 v[172:175], v241 offset:51200
	ds_read_b128 v[188:191], v241 offset:52224
	ds_read_b128 v[168:171], v241 offset:53248
	ds_read_b128 v[184:187], v241 offset:54272
	ds_read_b128 v[164:167], v241 offset:55296
	ds_read_b128 v[180:183], v241 offset:56320
.LBB0_527:
	s_mov_b32 m0, s62
	v_lshl_add_u64 v[2:3], v[2:3], 0, s[52:53]
	s_add_u32 s36, s36, 0x40080
	global_load_lds_dwordx4 v[2:3], off
	v_lshl_add_u64 v[2:3], v[208:209], 0, s[52:53]
	s_mov_b32 m0, s63
	s_addc_u32 s37, s37, 0
	global_load_lds_dwordx4 v[2:3], off
	v_lshl_add_u64 v[2:3], s[36:37], 0, v[198:199]
	s_mov_b32 m0, s68
	s_and_b64 vcc, exec, s[4:5]
	global_load_lds_dwordx4 v[2:3], off
	v_lshl_add_u64 v[2:3], s[36:37], 0, v[202:203]
	s_mov_b32 m0, s69
	s_nop 0
	global_load_lds_dwordx4 v[2:3], off
	v_lshl_add_u64 v[2:3], v[210:211], 0, s[52:53]
	s_mov_b32 m0, s64
	s_nop 0
	global_load_lds_dwordx4 v[2:3], off
	v_lshl_add_u64 v[2:3], v[220:221], 0, s[52:53]
	s_mov_b32 m0, s65
	s_nop 0
	global_load_lds_dwordx4 v[2:3], off
	s_waitcnt vmcnt(8)
	s_waitcnt lgkmcnt(0)
	s_barrier
	s_cbranch_vccnz .LBB0_520
	s_setprio 1
	s_waitcnt lgkmcnt(0)
	v_mfma_f32_16x16x32_bf16 v[64:67], v[148:151], v[176:179], v[64:67]
	v_mfma_f32_16x16x32_bf16 v[60:63], v[156:159], v[176:179], v[60:63]
	v_mfma_f32_16x16x32_bf16 v[48:51], v[148:151], v[172:175], v[48:51]
	v_mfma_f32_16x16x32_bf16 v[44:47], v[156:159], v[172:175], v[44:47]
	v_mfma_f32_16x16x32_bf16 v[32:35], v[148:151], v[168:171], v[32:35]
	v_mfma_f32_16x16x32_bf16 v[28:31], v[156:159], v[168:171], v[28:31]
	v_mfma_f32_16x16x32_bf16 v[16:19], v[148:151], v[164:167], v[16:19]
	v_mfma_f32_16x16x32_bf16 v[12:15], v[156:159], v[164:167], v[12:15]
	v_mfma_f32_16x16x32_bf16 v[64:67], v[152:155], v[192:195], v[64:67]
	v_mfma_f32_16x16x32_bf16 v[60:63], v[160:163], v[192:195], v[60:63]
	v_mfma_f32_16x16x32_bf16 v[48:51], v[152:155], v[188:191], v[48:51]
	v_mfma_f32_16x16x32_bf16 v[44:47], v[160:163], v[188:191], v[44:47]
	v_mfma_f32_16x16x32_bf16 v[32:35], v[152:155], v[184:187], v[32:35]
	v_mfma_f32_16x16x32_bf16 v[28:31], v[160:163], v[184:187], v[28:31]
	v_mfma_f32_16x16x32_bf16 v[16:19], v[152:155], v[180:183], v[16:19]
	v_mfma_f32_16x16x32_bf16 v[12:15], v[160:163], v[180:183], v[12:15]
	s_setprio 0
	s_setprio 1
	v_mfma_f32_16x16x32_bf16 v[56:59], v[132:135], v[176:179], v[56:59]
	v_mfma_f32_16x16x32_bf16 v[52:55], v[140:143], v[176:179], v[52:55]
	v_mfma_f32_16x16x32_bf16 v[40:43], v[132:135], v[172:175], v[40:43]
	v_mfma_f32_16x16x32_bf16 v[36:39], v[140:143], v[172:175], v[36:39]
	v_mfma_f32_16x16x32_bf16 v[24:27], v[132:135], v[168:171], v[24:27]
	v_mfma_f32_16x16x32_bf16 v[20:23], v[140:143], v[168:171], v[20:23]
	v_mfma_f32_16x16x32_bf16 v[8:11], v[132:135], v[164:167], v[8:11]
	v_mfma_f32_16x16x32_bf16 v[2:5], v[140:143], v[164:167], v[4:7]
	v_mfma_f32_16x16x32_bf16 v[56:59], v[136:139], v[192:195], v[56:59]
	v_mfma_f32_16x16x32_bf16 v[52:55], v[144:147], v[192:195], v[52:55]
	v_mfma_f32_16x16x32_bf16 v[40:43], v[136:139], v[188:191], v[40:43]
	v_mfma_f32_16x16x32_bf16 v[36:39], v[144:147], v[188:191], v[36:39]
	v_mfma_f32_16x16x32_bf16 v[24:27], v[136:139], v[184:187], v[24:27]
	v_mfma_f32_16x16x32_bf16 v[20:23], v[144:147], v[184:187], v[20:23]
	v_mfma_f32_16x16x32_bf16 v[8:11], v[136:139], v[180:183], v[8:11]
	v_mfma_f32_16x16x32_bf16 v[4:7], v[144:147], v[180:183], v[2:5]
	s_branch .LBB0_520

; #define PG8_STAGE(bufoff, gbase, voff) do { _Pragma("unroll") for (int _i = 0; _i < 2; ++_i) \
;         __builtin_amdgcn_global_load_lds((const unsigned*)((const char*)(gbase) + (voff)[_i]), (PG8_LAS unsigned*)(lds + (bufoff) + ldsw + _i * 8192), 16, 0, 0); } while (0)
; #define PG8_LDA(dst, b, h) do { _Pragma("unroll") for (int m = 0; m < 4; ++m) _Pragma("unroll") for (int k = 0; k < 2; ++k) dst[m][k] = *(const PG8_LAS bf16x8*)(lds + PG8_SA(b, h) + aoff + m * 2048 + k * 1024); } while (0)
; #define PG8_LDB(dst, b, h) do { _Pragma("unroll") for (int n = 0; n < 2; ++n) _Pragma("unroll") for (int k = 0; k < 2; ++k) dst[n][k] = *(const PG8_LAS bf16x8*)(lds + PG8_SB(b, h) + boff + n * 2048 + k * 1024); } while (0)
; #define PG8_MMA(ai, bj, At, Bt) do { __builtin_amdgcn_s_setprio(1); _Pragma("unroll") for (int m = 0; m < 4; ++m) _Pragma("unroll") for (int n = 0; n < 2; ++n) _Pragma("unroll") for (int k = 0; k < 2; ++k) \
;         acc[ai][bj][m][n] = __builtin_amdgcn_mfma_f32_16x16x32_bf16(Bt[n][k], At[m][k], acc[ai][bj][m][n], 0, 0, 0); __builtin_amdgcn_s_setprio(0); } while (0)
; #define PG8_WAIT_V(n) asm volatile("s_waitcnt vmcnt(" #n ")" ::: "memory")
; #define PG8_WAIT_L(n) asm volatile("s_waitcnt lgkmcnt(" #n ")" ::: "memory")
; #define PG8_BAR __builtin_amdgcn_s_barrier()
; #define PG8_SCHED __builtin_amdgcn_sched_barrier(0)
; template <class Epi, class Sched, bool ALIGN_EPI = false, bool SP2 = false>
; __device__ __forceinline__ void gemm_phase(PG8_LAS unsigned char* lds, const Gemm g, const Sched& S, const Epi& E) {
;     ...
;             const bool last = (t == nt - 2);
;             const char* a1 = cA + (size_t)(t + 1) * kstep;
;             const char* a2 = last ? nA : cA + (size_t)(t + 2) * kstep; const char* b2 = last ? nB : cB + (size_t)(t + 2) * kstep;
;             const char* a3 = a2 + kstep; const char* b3 = b2 + kstep;
;             if (last && has_next) S.a_ready(nxt);
;             if constexpr (SP2) {
;             PG8_LDB(B0, 0, 0); PG8_LDB(B1, 0, 1); PG8_SCHED; PG8_LDA(At, 0, 0); PG8_STAGE(PG8_SA(1, 1), a1 + hstep, voffA);
;             PG8_WAIT_V(8); PG8_WAIT_L(0); PG8_BAR; PG8_MMA(0, 0, At, B0); PG8_MMA(0, 1, At, B1); PG8_BAR; PG8_SCHED;
;             if (full) PG8_LDA(At, 0, 1); PG8_STAGE(PG8_SB(0, 0), b2, voffB); PG8_STAGE(PG8_SB(0, 1), b2 + hstep, voffB); PG8_STAGE(PG8_SA(0, 0), a2, voffA);
.LBB0_1038:
	s_add_u32 s27, s6, 0xfffe0080
	s_addc_u32 s28, s7, -1
	s_add_i32 s54, 0, 0x10000
	s_cmp_eq_u32 s25, 4
	s_cselect_b32 s31, s21, s28
	s_cselect_b32 s30, s20, s27
	v_add_u32_e32 v0, s54, v179
	s_cselect_b32 s29, s0, s19
	s_cselect_b32 s28, s1, s17
	s_add_i32 s27, 0, 0x14000
	ds_read_b128 v[144:147], v0
	ds_read_b128 v[148:151], v0 offset:1024
	ds_read_b128 v[152:155], v0 offset:2048
	ds_read_b128 v[156:159], v0 offset:3072
	v_add_u32_e32 v0, s27, v179
	ds_read_b128 v[160:163], v0
	ds_read_b128 v[164:167], v0 offset:1024
	ds_read_b128 v[168:171], v0 offset:2048
	ds_read_b128 v[172:175], v0 offset:3072
	v_lshl_add_u64 v[2:3], s[6:7], 0, v[140:141]
	s_add_i32 m0, s39, 0xc000
	ds_read_b128 v[182:185], v181
	ds_read_b128 v[186:189], v181 offset:1024
	ds_read_b128 v[190:193], v181 offset:2048
	ds_read_b128 v[194:197], v181 offset:3072
	ds_read_b128 v[198:201], v181 offset:4096
	ds_read_b128 v[202:205], v181 offset:5120
	ds_read_b128 v[206:209], v181 offset:6144
	ds_read_b128 v[220:223], v181 offset:7168
	global_load_lds_dwordx4 v[2:3], off
	v_lshl_add_u64 v[2:3], s[6:7], 0, v[142:143]
	s_add_i32 m0, s39, 0xe000
	s_nop 0
	global_load_lds_dwordx4 v[2:3], off
	s_waitcnt vmcnt(8)
	s_waitcnt lgkmcnt(0)
	s_barrier
	s_setprio 1
	s_waitcnt lgkmcnt(0)
	v_mfma_f32_16x16x32_bf16 v[128:131], v[144:147], v[182:185], v[128:131]
	v_mfma_f32_16x16x32_bf16 v[124:127], v[152:155], v[182:185], v[124:127]
	v_mfma_f32_16x16x32_bf16 v[120:123], v[144:147], v[190:193], v[120:123]
	v_mfma_f32_16x16x32_bf16 v[116:119], v[152:155], v[190:193], v[116:119]
	v_mfma_f32_16x16x32_bf16 v[112:115], v[144:147], v[198:201], v[112:115]
	v_mfma_f32_16x16x32_bf16 v[108:111], v[152:155], v[198:201], v[108:111]
	v_mfma_f32_16x16x32_bf16 v[104:107], v[144:147], v[206:209], v[104:107]
	v_mfma_f32_16x16x32_bf16 v[100:103], v[152:155], v[206:209], v[100:103]
	v_mfma_f32_16x16x32_bf16 v[128:131], v[148:151], v[186:189], v[128:131]
	v_mfma_f32_16x16x32_bf16 v[124:127], v[156:159], v[186:189], v[124:127]
	v_mfma_f32_16x16x32_bf16 v[120:123], v[148:151], v[194:197], v[120:123]
	v_mfma_f32_16x16x32_bf16 v[116:119], v[156:159], v[194:197], v[116:119]
	v_mfma_f32_16x16x32_bf16 v[112:115], v[148:151], v[202:205], v[112:115]
	v_mfma_f32_16x16x32_bf16 v[108:111], v[156:159], v[202:205], v[108:111]
	v_mfma_f32_16x16x32_bf16 v[104:107], v[148:151], v[220:223], v[104:107]
	v_mfma_f32_16x16x32_bf16 v[100:103], v[156:159], v[220:223], v[100:103]
	s_setprio 0
	s_setprio 1
	v_mfma_f32_16x16x32_bf16 v[96:99], v[160:163], v[182:185], v[96:99]
	v_mfma_f32_16x16x32_bf16 v[92:95], v[168:171], v[182:185], v[92:95]
	v_mfma_f32_16x16x32_bf16 v[88:91], v[160:163], v[190:193], v[88:91]
	v_mfma_f32_16x16x32_bf16 v[84:87], v[168:171], v[190:193], v[84:87]
	v_mfma_f32_16x16x32_bf16 v[80:83], v[160:163], v[198:201], v[80:83]
	v_mfma_f32_16x16x32_bf16 v[76:79], v[168:171], v[198:201], v[76:79]
	v_mfma_f32_16x16x32_bf16 v[72:75], v[160:163], v[206:209], v[72:75]
	v_mfma_f32_16x16x32_bf16 v[68:71], v[168:171], v[206:209], v[68:71]
	v_mfma_f32_16x16x32_bf16 v[96:99], v[164:167], v[186:189], v[96:99]
	v_mfma_f32_16x16x32_bf16 v[92:95], v[172:175], v[186:189], v[92:95]
	v_mfma_f32_16x16x32_bf16 v[88:91], v[164:167], v[194:197], v[88:91]
	v_mfma_f32_16x16x32_bf16 v[84:87], v[172:175], v[194:197], v[84:87]
	v_mfma_f32_16x16x32_bf16 v[80:83], v[164:167], v[202:205], v[80:83]
	v_mfma_f32_16x16x32_bf16 v[76:79], v[172:175], v[202:205], v[76:79]
	v_mfma_f32_16x16x32_bf16 v[72:75], v[164:167], v[220:223], v[72:75]
	v_mfma_f32_16x16x32_bf16 v[68:71], v[172:175], v[220:223], v[68:71]
	s_barrier
	s_setprio 0
	s_add_i32 s54, s54, s38
	v_lshl_add_u64 v[176:177], s[28:29], 0, v[134:135]
	s_mov_b32 m0, s54
	ds_read_b128 v[182:185], v181 offset:16384
	ds_read_b128 v[186:189], v181 offset:17408
	ds_read_b128 v[190:193], v181 offset:18432
	ds_read_b128 v[194:197], v181 offset:19456
	ds_read_b128 v[198:201], v181 offset:20480
	ds_read_b128 v[202:205], v181 offset:21504
	ds_read_b128 v[206:209], v181 offset:22528
	ds_read_b128 v[220:223], v181 offset:23552
	global_load_lds_dwordx4 v[176:177], off
	s_add_i32 m0, s54, 0x2000
	s_add_u32 s54, s28, 0x20000
	v_lshl_add_u64 v[210:211], s[28:29], 0, v[138:139]
	s_addc_u32 s55, s29, 0
	s_add_i32 s27, s27, s38
	global_load_lds_dwordx4 v[210:211], off
	v_lshl_add_u64 v[2:3], s[54:55], 0, v[134:135]
	s_mov_b32 m0, s27
	v_lshl_add_u64 v[212:213], s[30:31], 0, v[132:133]
	global_load_lds_dwordx4 v[2:3], off
	v_lshl_add_u64 v[2:3], s[54:55], 0, v[138:139]
	s_add_i32 m0, s27, 0x2000
	v_lshl_add_u64 v[214:215], s[30:31], 0, v[136:137]
	global_load_lds_dwordx4 v[2:3], off
	s_mov_b32 m0, s39
	s_nop 0
	global_load_lds_dwordx4 v[212:213], off
	s_mov_b32 m0, s40
	s_nop 0
	global_load_lds_dwordx4 v[214:215], off
	s_waitcnt vmcnt(8)
	s_waitcnt lgkmcnt(0)
	s_barrier
; #define PG8_STAGE(bufoff, gbase, voff) do { _Pragma("unroll") for (int _i = 0; _i < 2; ++_i) \
;         __builtin_amdgcn_global_load_lds((const unsigned*)((const char*)(gbase) + (voff)[_i]), (PG8_LAS unsigned*)(lds + (bufoff) + ldsw + _i * 8192), 16, 0, 0); } while (0)
; #define PG8_LDA(dst, b, h) do { _Pragma("unroll") for (int m = 0; m < 4; ++m) _Pragma("unroll") for (int k = 0; k < 2; ++k) dst[m][k] = *(const PG8_LAS bf16x8*)(lds + PG8_SA(b, h) + aoff + m * 2048 + k * 1024); } while (0)
; #define PG8_LDB(dst, b, h) do { _Pragma("unroll") for (int n = 0; n < 2; ++n) _Pragma("unroll") for (int k = 0; k < 2; ++k) dst[n][k] = *(const PG8_LAS bf16x8*)(lds + PG8_SB(b, h) + boff + n * 2048 + k * 1024); } while (0)
; #define PG8_MMA(ai, bj, At, Bt) do { __builtin_amdgcn_s_setprio(1); _Pragma("unroll") for (int m = 0; m < 4; ++m) _Pragma("unroll") for (int n = 0; n < 2; ++n) _Pragma("unroll") for (int k = 0; k < 2; ++k) \
;         acc[ai][bj][m][n] = __builtin_amdgcn_mfma_f32_16x16x32_bf16(Bt[n][k], At[m][k], acc[ai][bj][m][n], 0, 0, 0); __builtin_amdgcn_s_setprio(0); } while (0)
; #define PG8_WAIT_V(n) asm volatile("s_waitcnt vmcnt(" #n ")" ::: "memory")
; #define PG8_WAIT_L(n) asm volatile("s_waitcnt lgkmcnt(" #n ")" ::: "memory")
; #define PG8_BAR __builtin_amdgcn_s_barrier()
; #define PG8_SCHED __builtin_amdgcn_sched_barrier(0)
; template <class Epi, class Sched, bool ALIGN_EPI = false, bool SP2 = false>
; __device__ __forceinline__ void gemm_phase(PG8_LAS unsigned char* lds, const Gemm g, const Sched& S, const Epi& E) {
;     ...
;             PG8_WAIT_V(8); PG8_WAIT_L(0); PG8_BAR; if (full) { PG8_MMA(1, 0, At, B0); PG8_MMA(1, 1, At, B1); } PG8_BAR; PG8_SCHED;
;             PG8_LDB(B0, 1, 0); PG8_LDB(B1, 1, 1); PG8_SCHED; PG8_LDA(At, 1, 0); PG8_STAGE(PG8_SA(0, 1), a2 + hstep, voffA);
;             PG8_WAIT_V(8); PG8_WAIT_L(0); PG8_BAR; PG8_MMA(0, 0, At, B0); PG8_MMA(0, 1, At, B1); PG8_BAR; PG8_SCHED;
	s_setprio 1
	s_waitcnt lgkmcnt(0)
	v_mfma_f32_16x16x32_bf16 v[64:67], v[144:147], v[182:185], v[64:67]
	v_mfma_f32_16x16x32_bf16 v[60:63], v[152:155], v[182:185], v[60:63]
	v_mfma_f32_16x16x32_bf16 v[56:59], v[144:147], v[190:193], v[56:59]
	v_mfma_f32_16x16x32_bf16 v[52:55], v[152:155], v[190:193], v[52:55]
	v_mfma_f32_16x16x32_bf16 v[48:51], v[144:147], v[198:201], v[48:51]
	v_mfma_f32_16x16x32_bf16 v[44:47], v[152:155], v[198:201], v[44:47]
	v_mfma_f32_16x16x32_bf16 v[40:43], v[144:147], v[206:209], v[40:43]
	v_mfma_f32_16x16x32_bf16 v[36:39], v[152:155], v[206:209], v[36:39]
	v_mfma_f32_16x16x32_bf16 v[64:67], v[148:151], v[186:189], v[64:67]
	v_mfma_f32_16x16x32_bf16 v[60:63], v[156:159], v[186:189], v[60:63]
	v_mfma_f32_16x16x32_bf16 v[56:59], v[148:151], v[194:197], v[56:59]
	v_mfma_f32_16x16x32_bf16 v[52:55], v[156:159], v[194:197], v[52:55]
	v_mfma_f32_16x16x32_bf16 v[48:51], v[148:151], v[202:205], v[48:51]
	v_mfma_f32_16x16x32_bf16 v[44:47], v[156:159], v[202:205], v[44:47]
	v_mfma_f32_16x16x32_bf16 v[40:43], v[148:151], v[220:223], v[40:43]
	v_mfma_f32_16x16x32_bf16 v[36:39], v[156:159], v[220:223], v[36:39]
	s_setprio 0
	s_setprio 1
	v_mfma_f32_16x16x32_bf16 v[32:35], v[160:163], v[182:185], v[32:35]
	v_mfma_f32_16x16x32_bf16 v[28:31], v[168:171], v[182:185], v[28:31]
	v_mfma_f32_16x16x32_bf16 v[24:27], v[160:163], v[190:193], v[24:27]
	v_mfma_f32_16x16x32_bf16 v[20:23], v[168:171], v[190:193], v[20:23]
	v_mfma_f32_16x16x32_bf16 v[16:19], v[160:163], v[198:201], v[16:19]
	v_mfma_f32_16x16x32_bf16 v[12:15], v[168:171], v[198:201], v[12:15]
	v_mfma_f32_16x16x32_bf16 v[8:11], v[160:163], v[206:209], v[8:11]
	v_mfma_f32_16x16x32_bf16 v[2:5], v[168:171], v[206:209], v[4:7]
	v_mfma_f32_16x16x32_bf16 v[32:35], v[164:167], v[186:189], v[32:35]
	v_mfma_f32_16x16x32_bf16 v[28:31], v[172:175], v[186:189], v[28:31]
	v_mfma_f32_16x16x32_bf16 v[24:27], v[164:167], v[194:197], v[24:27]
	v_mfma_f32_16x16x32_bf16 v[20:23], v[172:175], v[194:197], v[20:23]
	v_mfma_f32_16x16x32_bf16 v[16:19], v[164:167], v[202:205], v[16:19]
	v_mfma_f32_16x16x32_bf16 v[12:15], v[172:175], v[202:205], v[12:15]
	v_mfma_f32_16x16x32_bf16 v[8:11], v[164:167], v[220:223], v[8:11]
	v_mfma_f32_16x16x32_bf16 v[2:5], v[172:175], v[220:223], v[2:5]
	s_barrier
	s_setprio 0
	s_add_i32 s27, 0, 0x18000
	v_add_u32_e32 v0, s27, v179
	s_add_i32 s54, 0, 0x1c000
	ds_read_b128 v[144:147], v0
	ds_read_b128 v[148:151], v0 offset:1024
	ds_read_b128 v[152:155], v0 offset:2048
	ds_read_b128 v[156:159], v0 offset:3072
	v_add_u32_e32 v0, s54, v179
	ds_read_b128 v[160:163], v0
	ds_read_b128 v[164:167], v0 offset:1024
	ds_read_b128 v[168:171], v0 offset:2048
	ds_read_b128 v[172:175], v0 offset:3072
	s_add_u32 s30, s30, 0x20000
	s_addc_u32 s31, s31, 0
	s_mov_b32 m0, s41
	v_lshl_add_u64 v[6:7], s[30:31], 0, v[132:133]
	ds_read_b128 v[182:185], v181 offset:32768
	ds_read_b128 v[186:189], v181 offset:33792
	ds_read_b128 v[190:193], v181 offset:34816
	ds_read_b128 v[194:197], v181 offset:35840
	ds_read_b128 v[198:201], v181 offset:36864
	ds_read_b128 v[202:205], v181 offset:37888
	ds_read_b128 v[206:209], v181 offset:38912
	ds_read_b128 v[220:223], v181 offset:39936
	global_load_lds_dwordx4 v[6:7], off
	v_lshl_add_u64 v[6:7], s[30:31], 0, v[136:137]
	s_mov_b32 m0, s42
	s_nop 0
	global_load_lds_dwordx4 v[6:7], off
	s_waitcnt vmcnt(8)
	s_waitcnt lgkmcnt(0)
	s_barrier
	s_setprio 1
	s_waitcnt lgkmcnt(0)
	v_mfma_f32_16x16x32_bf16 v[128:131], v[144:147], v[182:185], v[128:131]
	v_mfma_f32_16x16x32_bf16 v[124:127], v[152:155], v[182:185], v[124:127]
	v_mfma_f32_16x16x32_bf16 v[120:123], v[144:147], v[190:193], v[120:123]
	v_mfma_f32_16x16x32_bf16 v[116:119], v[152:155], v[190:193], v[116:119]
	v_mfma_f32_16x16x32_bf16 v[112:115], v[144:147], v[198:201], v[112:115]
	v_mfma_f32_16x16x32_bf16 v[108:111], v[152:155], v[198:201], v[108:111]
	v_mfma_f32_16x16x32_bf16 v[104:107], v[144:147], v[206:209], v[104:107]
	v_mfma_f32_16x16x32_bf16 v[100:103], v[152:155], v[206:209], v[100:103]
	v_mfma_f32_16x16x32_bf16 v[128:131], v[148:151], v[186:189], v[128:131]
	v_mfma_f32_16x16x32_bf16 v[124:127], v[156:159], v[186:189], v[124:127]
	v_mfma_f32_16x16x32_bf16 v[120:123], v[148:151], v[194:197], v[120:123]
	v_mfma_f32_16x16x32_bf16 v[116:119], v[156:159], v[194:197], v[116:119]
	v_mfma_f32_16x16x32_bf16 v[112:115], v[148:151], v[202:205], v[112:115]
	v_mfma_f32_16x16x32_bf16 v[108:111], v[156:159], v[202:205], v[108:111]
	v_mfma_f32_16x16x32_bf16 v[104:107], v[148:151], v[220:223], v[104:107]
	v_mfma_f32_16x16x32_bf16 v[100:103], v[156:159], v[220:223], v[100:103]
	s_setprio 0
	s_setprio 1
	v_mfma_f32_16x16x32_bf16 v[96:99], v[160:163], v[182:185], v[96:99]
	v_mfma_f32_16x16x32_bf16 v[92:95], v[168:171], v[182:185], v[92:95]
	v_mfma_f32_16x16x32_bf16 v[88:91], v[160:163], v[190:193], v[88:91]
	v_mfma_f32_16x16x32_bf16 v[84:87], v[168:171], v[190:193], v[84:87]
	v_mfma_f32_16x16x32_bf16 v[80:83], v[160:163], v[198:201], v[80:83]
	v_mfma_f32_16x16x32_bf16 v[76:79], v[168:171], v[198:201], v[76:79]
	v_mfma_f32_16x16x32_bf16 v[72:75], v[160:163], v[206:209], v[72:75]
	v_mfma_f32_16x16x32_bf16 v[68:71], v[168:171], v[206:209], v[68:71]
	v_mfma_f32_16x16x32_bf16 v[96:99], v[164:167], v[186:189], v[96:99]
	v_mfma_f32_16x16x32_bf16 v[92:95], v[172:175], v[186:189], v[92:95]
	v_mfma_f32_16x16x32_bf16 v[88:91], v[164:167], v[194:197], v[88:91]
	v_mfma_f32_16x16x32_bf16 v[84:87], v[172:175], v[194:197], v[84:87]
	v_mfma_f32_16x16x32_bf16 v[80:83], v[164:167], v[202:205], v[80:83]
	v_mfma_f32_16x16x32_bf16 v[76:79], v[172:175], v[202:205], v[76:79]
	v_mfma_f32_16x16x32_bf16 v[72:75], v[164:167], v[220:223], v[72:75]
	v_mfma_f32_16x16x32_bf16 v[68:71], v[172:175], v[220:223], v[68:71]
	s_barrier
; #define PG8_STAGE(bufoff, gbase, voff) do { _Pragma("unroll") for (int _i = 0; _i < 2; ++_i) \
;         __builtin_amdgcn_global_load_lds((const unsigned*)((const char*)(gbase) + (voff)[_i]), (PG8_LAS unsigned*)(lds + (bufoff) + ldsw + _i * 8192), 16, 0, 0); } while (0)
; #define PG8_LDA(dst, b, h) do { _Pragma("unroll") for (int m = 0; m < 4; ++m) _Pragma("unroll") for (int k = 0; k < 2; ++k) dst[m][k] = *(const PG8_LAS bf16x8*)(lds + PG8_SA(b, h) + aoff + m * 2048 + k * 1024); } while (0)
; #define PG8_MMA(ai, bj, At, Bt) do { __builtin_amdgcn_s_setprio(1); _Pragma("unroll") for (int m = 0; m < 4; ++m) _Pragma("unroll") for (int n = 0; n < 2; ++n) _Pragma("unroll") for (int k = 0; k < 2; ++k) \
;         acc[ai][bj][m][n] = __builtin_amdgcn_mfma_f32_16x16x32_bf16(Bt[n][k], At[m][k], acc[ai][bj][m][n], 0, 0, 0); __builtin_amdgcn_s_setprio(0); } while (0)
; #define PG8_WAIT_V(n) asm volatile("s_waitcnt vmcnt(" #n ")" ::: "memory")
; #define PG8_WAIT_L(n) asm volatile("s_waitcnt lgkmcnt(" #n ")" ::: "memory")
; #define PG8_BAR __builtin_amdgcn_s_barrier()
; #define PG8_SCHED __builtin_amdgcn_sched_barrier(0)
; template <class Epi, class Sched, bool ALIGN_EPI = false, bool SP2 = false>
; __device__ __forceinline__ void gemm_phase(PG8_LAS unsigned char* lds, const Gemm g, const Sched& S, const Epi& E) {
;     ...
;             if (full) PG8_LDA(At, 1, 1); PG8_STAGE(PG8_SB(1, 0), b3, voffB); PG8_STAGE(PG8_SB(1, 1), b3 + hstep, voffB); PG8_STAGE(PG8_SA(1, 0), a3, voffA);
;             PG8_WAIT_V(8); PG8_WAIT_L(0); PG8_BAR; if (full) { PG8_MMA(1, 0, At, B0); PG8_MMA(1, 1, At, B1); } PG8_BAR; PG8_SCHED;
;     ...
;         if constexpr (ALIGN_EPI) { if (wr == 0) PG8_BAR; }
	s_setprio 0
	s_add_i32 s27, s27, s38
	v_lshl_add_u64 v[6:7], v[176:177], 0, s[52:53]
	s_mov_b32 m0, s27
	ds_read_b128 v[182:185], v181 offset:49152
	ds_read_b128 v[186:189], v181 offset:50176
	ds_read_b128 v[190:193], v181 offset:51200
	ds_read_b128 v[194:197], v181 offset:52224
	ds_read_b128 v[198:201], v181 offset:53248
	ds_read_b128 v[202:205], v181 offset:54272
	ds_read_b128 v[206:209], v181 offset:55296
	ds_read_b128 v[220:223], v181 offset:56320
	global_load_lds_dwordx4 v[6:7], off
	s_add_i32 m0, s27, 0x2000
	s_add_u32 s28, s28, 0x20080
	v_lshl_add_u64 v[6:7], v[210:211], 0, s[52:53]
	s_addc_u32 s29, s29, 0
	s_add_i32 s27, s54, s38
	global_load_lds_dwordx4 v[6:7], off
	v_lshl_add_u64 v[6:7], s[28:29], 0, v[134:135]
	s_mov_b32 m0, s27
	s_nop 0
	global_load_lds_dwordx4 v[6:7], off
	v_lshl_add_u64 v[6:7], s[28:29], 0, v[138:139]
	s_add_i32 m0, s27, 0x2000
	s_nop 0
	global_load_lds_dwordx4 v[6:7], off
	v_lshl_add_u64 v[6:7], v[212:213], 0, s[52:53]
	s_mov_b32 m0, s43
	s_nop 0
	global_load_lds_dwordx4 v[6:7], off
	v_lshl_add_u64 v[6:7], v[214:215], 0, s[52:53]
	s_mov_b32 m0, s44
	s_nop 0
	global_load_lds_dwordx4 v[6:7], off
	s_waitcnt vmcnt(8)
	s_waitcnt lgkmcnt(0)
	s_barrier
	s_setprio 1
	s_waitcnt lgkmcnt(0)
	v_mfma_f32_16x16x32_bf16 v[64:67], v[144:147], v[182:185], v[64:67]
	v_mfma_f32_16x16x32_bf16 v[60:63], v[152:155], v[182:185], v[60:63]
	v_mfma_f32_16x16x32_bf16 v[56:59], v[144:147], v[190:193], v[56:59]
	v_mfma_f32_16x16x32_bf16 v[52:55], v[152:155], v[190:193], v[52:55]
	v_mfma_f32_16x16x32_bf16 v[48:51], v[144:147], v[198:201], v[48:51]
	v_mfma_f32_16x16x32_bf16 v[44:47], v[152:155], v[198:201], v[44:47]
	v_mfma_f32_16x16x32_bf16 v[40:43], v[144:147], v[206:209], v[40:43]
	v_mfma_f32_16x16x32_bf16 v[36:39], v[152:155], v[206:209], v[36:39]
	v_mfma_f32_16x16x32_bf16 v[64:67], v[148:151], v[186:189], v[64:67]
	v_mfma_f32_16x16x32_bf16 v[60:63], v[156:159], v[186:189], v[60:63]
	v_mfma_f32_16x16x32_bf16 v[56:59], v[148:151], v[194:197], v[56:59]
	v_mfma_f32_16x16x32_bf16 v[52:55], v[156:159], v[194:197], v[52:55]
	v_mfma_f32_16x16x32_bf16 v[48:51], v[148:151], v[202:205], v[48:51]
	v_mfma_f32_16x16x32_bf16 v[44:47], v[156:159], v[202:205], v[44:47]
	v_mfma_f32_16x16x32_bf16 v[40:43], v[148:151], v[220:223], v[40:43]
	v_mfma_f32_16x16x32_bf16 v[36:39], v[156:159], v[220:223], v[36:39]
	s_setprio 0
	s_setprio 1
	v_mfma_f32_16x16x32_bf16 v[32:35], v[160:163], v[182:185], v[32:35]
	v_mfma_f32_16x16x32_bf16 v[28:31], v[168:171], v[182:185], v[28:31]
	v_mfma_f32_16x16x32_bf16 v[24:27], v[160:163], v[190:193], v[24:27]
	v_mfma_f32_16x16x32_bf16 v[20:23], v[168:171], v[190:193], v[20:23]
	v_mfma_f32_16x16x32_bf16 v[16:19], v[160:163], v[198:201], v[16:19]
	v_mfma_f32_16x16x32_bf16 v[12:15], v[168:171], v[198:201], v[12:15]
	v_mfma_f32_16x16x32_bf16 v[6:9], v[160:163], v[206:209], v[8:11]
	v_mfma_f32_16x16x32_bf16 v[2:5], v[168:171], v[206:209], v[2:5]
	v_mfma_f32_16x16x32_bf16 v[32:35], v[164:167], v[186:189], v[32:35]
	v_mfma_f32_16x16x32_bf16 v[28:31], v[172:175], v[186:189], v[28:31]
	v_mfma_f32_16x16x32_bf16 v[24:27], v[164:167], v[194:197], v[24:27]
	v_mfma_f32_16x16x32_bf16 v[20:23], v[172:175], v[194:197], v[20:23]
	v_mfma_f32_16x16x32_bf16 v[16:19], v[164:167], v[202:205], v[16:19]
	v_mfma_f32_16x16x32_bf16 v[12:15], v[172:175], v[202:205], v[12:15]
	v_mfma_f32_16x16x32_bf16 v[8:11], v[164:167], v[220:223], v[6:9]
	v_mfma_f32_16x16x32_bf16 v[4:7], v[172:175], v[220:223], v[2:5]
	s_barrier
	s_setprio 0
	s_add_i32 s25, s25, 2
	s_add_u32 s6, s6, 0x100
	s_addc_u32 s7, s7, 0
	s_add_u32 s17, s17, 0x100
	s_addc_u32 s19, s19, 0
	s_cmp_gt_u32 s25, 5
	s_cbranch_scc0 .LBB0_1038
	s_and_b64 vcc, exec, s[14:15]
	s_cbranch_vccz .LBB0_1041
	s_barrier

; #define PG8_STAGE(bufoff, gbase, voff) do { _Pragma("unroll") for (int _i = 0; _i < 2; ++_i) \
;         __builtin_amdgcn_global_load_lds((const unsigned*)((const char*)(gbase) + (voff)[_i]), (PG8_LAS unsigned*)(lds + (bufoff) + ldsw + _i * 8192), 16, 0, 0); } while (0)
; #define PG8_LDA(dst, b, h) do { _Pragma("unroll") for (int m = 0; m < 4; ++m) _Pragma("unroll") for (int k = 0; k < 2; ++k) dst[m][k] = *(const PG8_LAS bf16x8*)(lds + PG8_SA(b, h) + aoff + m * 2048 + k * 1024); } while (0)
; #define PG8_LDB(dst, b, h) do { _Pragma("unroll") for (int n = 0; n < 2; ++n) _Pragma("unroll") for (int k = 0; k < 2; ++k) dst[n][k] = *(const PG8_LAS bf16x8*)(lds + PG8_SB(b, h) + boff + n * 2048 + k * 1024); } while (0)
; #define PG8_MMA(ai, bj, At, Bt) do { __builtin_amdgcn_s_setprio(1); _Pragma("unroll") for (int m = 0; m < 4; ++m) _Pragma("unroll") for (int n = 0; n < 2; ++n) _Pragma("unroll") for (int k = 0; k < 2; ++k) \
;         acc[ai][bj][m][n] = __builtin_amdgcn_mfma_f32_16x16x32_bf16(Bt[n][k], At[m][k], acc[ai][bj][m][n], 0, 0, 0); __builtin_amdgcn_s_setprio(0); } while (0)
; #define PG8_WAIT_V(n) asm volatile("s_waitcnt vmcnt(" #n ")" ::: "memory")
; #define PG8_WAIT_L(n) asm volatile("s_waitcnt lgkmcnt(" #n ")" ::: "memory")
; #define PG8_BAR __builtin_amdgcn_s_barrier()
; #define PG8_SCHED __builtin_amdgcn_sched_barrier(0)
; template <class Epi, class Sched, bool ALIGN_EPI = false, bool SP2 = false>
; __device__ __forceinline__ void gemm_phase(PG8_LAS unsigned char* lds, const Gemm g, const Sched& S, const Epi& E) {
;     ...
;             const bool last = (t == nt - 2);
;             const char* a1 = cA + (size_t)(t + 1) * kstep;
;             const char* a2 = last ? nA : cA + (size_t)(t + 2) * kstep; const char* b2 = last ? nB : cB + (size_t)(t + 2) * kstep;
;             const char* a3 = a2 + kstep; const char* b3 = b2 + kstep;
;             if (last && has_next) S.a_ready(nxt);
;             if constexpr (SP2) {
;             PG8_LDB(B0, 0, 0); PG8_LDB(B1, 0, 1); PG8_SCHED; PG8_LDA(At, 0, 0); PG8_STAGE(PG8_SA(1, 1), a1 + hstep, voffA);
;             PG8_WAIT_V(8); PG8_WAIT_L(0); PG8_BAR; PG8_MMA(0, 0, At, B0); PG8_MMA(0, 1, At, B1); PG8_BAR; PG8_SCHED;
;             if (full) PG8_LDA(At, 0, 1); PG8_STAGE(PG8_SB(0, 0), b2, voffB); PG8_STAGE(PG8_SB(0, 1), b2 + hstep, voffB); PG8_STAGE(PG8_SA(0, 0), a2, voffA);
.LBB0_1149:
	s_add_u32 s30, s18, s28
	s_addc_u32 s31, s19, s29
	s_add_u32 s30, s30, 0x100
	s_addc_u32 s31, s31, 0
	s_add_u32 s62, s57, s28
	s_addc_u32 s63, s58, s29
	s_add_i32 s64, 0, 0x10000
	s_cmpk_eq_i32 s28, 0x700
	s_cselect_b32 s35, s23, s31
	s_cselect_b32 s34, s59, s30
	v_add_u32_e32 v143, s64, v140
	s_cselect_b32 s31, s21, s63
	s_cselect_b32 s30, s60, s62
	s_add_i32 s65, 0, 0x14000
	ds_read_b128 v[144:147], v143
	ds_read_b128 v[148:151], v143 offset:1024
	ds_read_b128 v[152:155], v143 offset:2048
	ds_read_b128 v[156:159], v143 offset:3072
	v_add_u32_e32 v143, s65, v140
	ds_read_b128 v[160:163], v143
	ds_read_b128 v[164:167], v143 offset:1024
	ds_read_b128 v[168:171], v143 offset:2048
	ds_read_b128 v[174:177], v143 offset:3072
	v_lshl_add_u64 v[210:211], v[136:137], 0, s[28:29]
	s_add_i32 m0, s41, 0xc000
	ds_read_b128 v[178:181], v141
	ds_read_b128 v[182:185], v141 offset:1024
	ds_read_b128 v[186:189], v141 offset:2048
	ds_read_b128 v[190:193], v141 offset:3072
	ds_read_b128 v[194:197], v141 offset:4096
	ds_read_b128 v[198:201], v141 offset:5120
	ds_read_b128 v[202:205], v141 offset:6144
	ds_read_b128 v[206:209], v141 offset:7168
	global_load_lds_dwordx4 v[210:211], off
	v_lshl_add_u64 v[210:211], v[138:139], 0, s[28:29]
	s_add_i32 m0, s41, 0xe000
	s_nop 0
	global_load_lds_dwordx4 v[210:211], off
	s_waitcnt vmcnt(8)
	s_waitcnt lgkmcnt(0)
	s_barrier
	s_setprio 1
	s_waitcnt lgkmcnt(0)
	v_mfma_f32_16x16x32_bf16 v[126:129], v[144:147], v[178:181], v[126:129]
	v_mfma_f32_16x16x32_bf16 v[86:89], v[152:155], v[178:181], v[86:89]
	v_mfma_f32_16x16x32_bf16 v[114:117], v[144:147], v[186:189], v[114:117]
	v_mfma_f32_16x16x32_bf16 v[82:85], v[152:155], v[186:189], v[82:85]
	v_mfma_f32_16x16x32_bf16 v[122:125], v[144:147], v[194:197], v[122:125]
	v_mfma_f32_16x16x32_bf16 v[106:109], v[152:155], v[194:197], v[106:109]
	v_mfma_f32_16x16x32_bf16 v[118:121], v[144:147], v[202:205], v[118:121]
	v_mfma_f32_16x16x32_bf16 v[110:113], v[152:155], v[202:205], v[110:113]
	v_mfma_f32_16x16x32_bf16 v[126:129], v[148:151], v[182:185], v[126:129]
	v_mfma_f32_16x16x32_bf16 v[86:89], v[156:159], v[182:185], v[86:89]
	v_mfma_f32_16x16x32_bf16 v[114:117], v[148:151], v[190:193], v[114:117]
	v_mfma_f32_16x16x32_bf16 v[82:85], v[156:159], v[190:193], v[82:85]
	v_mfma_f32_16x16x32_bf16 v[122:125], v[148:151], v[198:201], v[122:125]
	v_mfma_f32_16x16x32_bf16 v[106:109], v[156:159], v[198:201], v[106:109]
	v_mfma_f32_16x16x32_bf16 v[118:121], v[148:151], v[206:209], v[118:121]
	v_mfma_f32_16x16x32_bf16 v[110:113], v[156:159], v[206:209], v[110:113]
	s_setprio 0
	s_setprio 1
	v_mfma_f32_16x16x32_bf16 v[22:25], v[160:163], v[178:181], v[22:25]
	v_mfma_f32_16x16x32_bf16 v[6:9], v[168:171], v[178:181], v[6:9]
	v_mfma_f32_16x16x32_bf16 v[18:21], v[160:163], v[186:189], v[18:21]
	v_mfma_f32_16x16x32_bf16 v[2:5], v[168:171], v[186:189], v[2:5]
	v_mfma_f32_16x16x32_bf16 v[38:41], v[160:163], v[194:197], v[38:41]
	v_mfma_f32_16x16x32_bf16 v[10:13], v[168:171], v[194:197], v[10:13]
	v_mfma_f32_16x16x32_bf16 v[34:37], v[160:163], v[202:205], v[34:37]
	v_mfma_f32_16x16x32_bf16 v[14:17], v[168:171], v[202:205], v[14:17]
	v_mfma_f32_16x16x32_bf16 v[22:25], v[164:167], v[182:185], v[22:25]
	v_mfma_f32_16x16x32_bf16 v[6:9], v[174:177], v[182:185], v[6:9]
	v_mfma_f32_16x16x32_bf16 v[18:21], v[164:167], v[190:193], v[18:21]
	v_mfma_f32_16x16x32_bf16 v[2:5], v[174:177], v[190:193], v[2:5]
	v_mfma_f32_16x16x32_bf16 v[38:41], v[164:167], v[198:201], v[38:41]
	v_mfma_f32_16x16x32_bf16 v[10:13], v[174:177], v[198:201], v[10:13]
	v_mfma_f32_16x16x32_bf16 v[34:37], v[164:167], v[206:209], v[34:37]
	v_mfma_f32_16x16x32_bf16 v[14:17], v[174:177], v[206:209], v[14:17]
	s_barrier
	s_setprio 0
	s_add_i32 s62, s64, s40
	v_lshl_add_u64 v[210:211], s[30:31], 0, v[0:1]
	s_mov_b32 m0, s62
	ds_read_b128 v[178:181], v141 offset:16384
	ds_read_b128 v[182:185], v141 offset:17408
	ds_read_b128 v[186:189], v141 offset:18432
	ds_read_b128 v[190:193], v141 offset:19456
	ds_read_b128 v[194:197], v141 offset:20480
	ds_read_b128 v[198:201], v141 offset:21504
	ds_read_b128 v[202:205], v141 offset:22528
	ds_read_b128 v[206:209], v141 offset:23552
	global_load_lds_dwordx4 v[210:211], off
	s_add_i32 m0, s62, 0x2000
	s_add_u32 s62, s30, 0x40000
	v_lshl_add_u64 v[212:213], s[30:31], 0, v[130:131]
	s_addc_u32 s63, s31, 0
	s_add_i32 s64, s65, s40
	global_load_lds_dwordx4 v[212:213], off
	v_lshl_add_u64 v[214:215], s[62:63], 0, v[0:1]
	s_mov_b32 m0, s64
	v_lshl_add_u64 v[220:221], s[34:35], 0, v[130:131]
	global_load_lds_dwordx4 v[214:215], off
	v_lshl_add_u64 v[214:215], s[62:63], 0, v[130:131]
	s_add_i32 m0, s64, 0x2000
	s_nop 0
	global_load_lds_dwordx4 v[214:215], off
	v_lshl_add_u64 v[214:215], s[34:35], 0, v[0:1]
	s_mov_b32 m0, s41
	s_nop 0
	global_load_lds_dwordx4 v[214:215], off
	s_mov_b32 m0, s42
	s_nop 0
	global_load_lds_dwordx4 v[220:221], off
	s_waitcnt vmcnt(8)
	s_waitcnt lgkmcnt(0)
	s_barrier
; #define PG8_STAGE(bufoff, gbase, voff) do { _Pragma("unroll") for (int _i = 0; _i < 2; ++_i) \
;         __builtin_amdgcn_global_load_lds((const unsigned*)((const char*)(gbase) + (voff)[_i]), (PG8_LAS unsigned*)(lds + (bufoff) + ldsw + _i * 8192), 16, 0, 0); } while (0)
; #define PG8_LDA(dst, b, h) do { _Pragma("unroll") for (int m = 0; m < 4; ++m) _Pragma("unroll") for (int k = 0; k < 2; ++k) dst[m][k] = *(const PG8_LAS bf16x8*)(lds + PG8_SA(b, h) + aoff + m * 2048 + k * 1024); } while (0)
; #define PG8_LDB(dst, b, h) do { _Pragma("unroll") for (int n = 0; n < 2; ++n) _Pragma("unroll") for (int k = 0; k < 2; ++k) dst[n][k] = *(const PG8_LAS bf16x8*)(lds + PG8_SB(b, h) + boff + n * 2048 + k * 1024); } while (0)
; #define PG8_MMA(ai, bj, At, Bt) do { __builtin_amdgcn_s_setprio(1); _Pragma("unroll") for (int m = 0; m < 4; ++m) _Pragma("unroll") for (int n = 0; n < 2; ++n) _Pragma("unroll") for (int k = 0; k < 2; ++k) \
;         acc[ai][bj][m][n] = __builtin_amdgcn_mfma_f32_16x16x32_bf16(Bt[n][k], At[m][k], acc[ai][bj][m][n], 0, 0, 0); __builtin_amdgcn_s_setprio(0); } while (0)
; #define PG8_WAIT_V(n) asm volatile("s_waitcnt vmcnt(" #n ")" ::: "memory")
; #define PG8_WAIT_L(n) asm volatile("s_waitcnt lgkmcnt(" #n ")" ::: "memory")
; #define PG8_BAR __builtin_amdgcn_s_barrier()
; #define PG8_SCHED __builtin_amdgcn_sched_barrier(0)
; template <class Epi, class Sched, bool ALIGN_EPI = false, bool SP2 = false>
; __device__ __forceinline__ void gemm_phase(PG8_LAS unsigned char* lds, const Gemm g, const Sched& S, const Epi& E) {
;     ...
;             PG8_WAIT_V(8); PG8_WAIT_L(0); PG8_BAR; if (full) { PG8_MMA(1, 0, At, B0); PG8_MMA(1, 1, At, B1); } PG8_BAR; PG8_SCHED;
;             PG8_LDB(B0, 1, 0); PG8_LDB(B1, 1, 1); PG8_SCHED; PG8_LDA(At, 1, 0); PG8_STAGE(PG8_SA(0, 1), a2 + hstep, voffA);
;             PG8_WAIT_V(8); PG8_WAIT_L(0); PG8_BAR; PG8_MMA(0, 0, At, B0); PG8_MMA(0, 1, At, B1); PG8_BAR; PG8_SCHED;
	s_setprio 1
	s_waitcnt lgkmcnt(0)
	v_mfma_f32_16x16x32_bf16 v[102:105], v[144:147], v[178:181], v[102:105]
	v_mfma_f32_16x16x32_bf16 v[98:101], v[152:155], v[178:181], v[98:101]
	v_mfma_f32_16x16x32_bf16 v[94:97], v[144:147], v[186:189], v[94:97]
	v_mfma_f32_16x16x32_bf16 v[90:93], v[152:155], v[186:189], v[90:93]
	v_mfma_f32_16x16x32_bf16 v[78:81], v[144:147], v[194:197], v[78:81]
	v_mfma_f32_16x16x32_bf16 v[74:77], v[152:155], v[194:197], v[74:77]
	v_mfma_f32_16x16x32_bf16 v[70:73], v[144:147], v[202:205], v[70:73]
	v_mfma_f32_16x16x32_bf16 v[66:69], v[152:155], v[202:205], v[66:69]
	v_mfma_f32_16x16x32_bf16 v[102:105], v[148:151], v[182:185], v[102:105]
	v_mfma_f32_16x16x32_bf16 v[98:101], v[156:159], v[182:185], v[98:101]
	v_mfma_f32_16x16x32_bf16 v[94:97], v[148:151], v[190:193], v[94:97]
	v_mfma_f32_16x16x32_bf16 v[90:93], v[156:159], v[190:193], v[90:93]
	v_mfma_f32_16x16x32_bf16 v[78:81], v[148:151], v[198:201], v[78:81]
	v_mfma_f32_16x16x32_bf16 v[74:77], v[156:159], v[198:201], v[74:77]
	v_mfma_f32_16x16x32_bf16 v[70:73], v[148:151], v[206:209], v[70:73]
	v_mfma_f32_16x16x32_bf16 v[66:69], v[156:159], v[206:209], v[66:69]
	s_setprio 0
	s_setprio 1
	v_mfma_f32_16x16x32_bf16 v[50:53], v[160:163], v[178:181], v[50:53]
	v_mfma_f32_16x16x32_bf16 v[26:29], v[168:171], v[178:181], v[26:29]
	v_mfma_f32_16x16x32_bf16 v[46:49], v[160:163], v[186:189], v[46:49]
	v_mfma_f32_16x16x32_bf16 v[30:33], v[168:171], v[186:189], v[30:33]
	v_mfma_f32_16x16x32_bf16 v[62:65], v[160:163], v[194:197], v[62:65]
	v_mfma_f32_16x16x32_bf16 v[54:57], v[168:171], v[194:197], v[54:57]
	v_mfma_f32_16x16x32_bf16 v[58:61], v[160:163], v[202:205], v[58:61]
	v_mfma_f32_16x16x32_bf16 v[42:45], v[168:171], v[202:205], v[42:45]
	v_mfma_f32_16x16x32_bf16 v[50:53], v[164:167], v[182:185], v[50:53]
	v_mfma_f32_16x16x32_bf16 v[26:29], v[174:177], v[182:185], v[26:29]
	v_mfma_f32_16x16x32_bf16 v[46:49], v[164:167], v[190:193], v[46:49]
	v_mfma_f32_16x16x32_bf16 v[30:33], v[174:177], v[190:193], v[30:33]
	v_mfma_f32_16x16x32_bf16 v[62:65], v[164:167], v[198:201], v[62:65]
	v_mfma_f32_16x16x32_bf16 v[54:57], v[174:177], v[198:201], v[54:57]
	v_mfma_f32_16x16x32_bf16 v[58:61], v[164:167], v[206:209], v[58:61]
	v_mfma_f32_16x16x32_bf16 v[42:45], v[174:177], v[206:209], v[42:45]
	s_barrier
	s_setprio 0
	s_add_i32 s62, 0, 0x18000
	v_add_u32_e32 v143, s62, v140
	s_add_i32 s63, 0, 0x1c000
	ds_read_b128 v[144:147], v143
	ds_read_b128 v[148:151], v143 offset:1024
	ds_read_b128 v[152:155], v143 offset:2048
	ds_read_b128 v[156:159], v143 offset:3072
	v_add_u32_e32 v143, s63, v140
	ds_read_b128 v[160:163], v143
	ds_read_b128 v[164:167], v143 offset:1024
	ds_read_b128 v[168:171], v143 offset:2048
	ds_read_b128 v[174:177], v143 offset:3072
	s_add_u32 s34, s34, 0x40000
	s_addc_u32 s35, s35, 0
	s_mov_b32 m0, s43
	v_lshl_add_u64 v[222:223], s[34:35], 0, v[0:1]
	ds_read_b128 v[178:181], v141 offset:32768
	ds_read_b128 v[182:185], v141 offset:33792
	ds_read_b128 v[186:189], v141 offset:34816
	ds_read_b128 v[190:193], v141 offset:35840
	ds_read_b128 v[194:197], v141 offset:36864
	ds_read_b128 v[198:201], v141 offset:37888
	ds_read_b128 v[202:205], v141 offset:38912
	ds_read_b128 v[206:209], v141 offset:39936
	global_load_lds_dwordx4 v[222:223], off
	v_lshl_add_u64 v[222:223], s[34:35], 0, v[130:131]
	s_mov_b32 m0, s44
	s_nop 0
	global_load_lds_dwordx4 v[222:223], off
	s_waitcnt vmcnt(8)
	s_waitcnt lgkmcnt(0)
	s_barrier
	s_setprio 1
	s_waitcnt lgkmcnt(0)
	v_mfma_f32_16x16x32_bf16 v[126:129], v[144:147], v[178:181], v[126:129]
	v_mfma_f32_16x16x32_bf16 v[86:89], v[152:155], v[178:181], v[86:89]
	v_mfma_f32_16x16x32_bf16 v[114:117], v[144:147], v[186:189], v[114:117]
	v_mfma_f32_16x16x32_bf16 v[82:85], v[152:155], v[186:189], v[82:85]
	v_mfma_f32_16x16x32_bf16 v[122:125], v[144:147], v[194:197], v[122:125]
	v_mfma_f32_16x16x32_bf16 v[106:109], v[152:155], v[194:197], v[106:109]
	v_mfma_f32_16x16x32_bf16 v[118:121], v[144:147], v[202:205], v[118:121]
	v_mfma_f32_16x16x32_bf16 v[110:113], v[152:155], v[202:205], v[110:113]
	v_mfma_f32_16x16x32_bf16 v[126:129], v[148:151], v[182:185], v[126:129]
	v_mfma_f32_16x16x32_bf16 v[86:89], v[156:159], v[182:185], v[86:89]
	v_mfma_f32_16x16x32_bf16 v[114:117], v[148:151], v[190:193], v[114:117]
	v_mfma_f32_16x16x32_bf16 v[82:85], v[156:159], v[190:193], v[82:85]
	v_mfma_f32_16x16x32_bf16 v[122:125], v[148:151], v[198:201], v[122:125]
	v_mfma_f32_16x16x32_bf16 v[106:109], v[156:159], v[198:201], v[106:109]
	v_mfma_f32_16x16x32_bf16 v[118:121], v[148:151], v[206:209], v[118:121]
	v_mfma_f32_16x16x32_bf16 v[110:113], v[156:159], v[206:209], v[110:113]
	s_setprio 0
	s_setprio 1
	v_mfma_f32_16x16x32_bf16 v[22:25], v[160:163], v[178:181], v[22:25]
	v_mfma_f32_16x16x32_bf16 v[6:9], v[168:171], v[178:181], v[6:9]
	v_mfma_f32_16x16x32_bf16 v[18:21], v[160:163], v[186:189], v[18:21]
	v_mfma_f32_16x16x32_bf16 v[2:5], v[168:171], v[186:189], v[2:5]
	v_mfma_f32_16x16x32_bf16 v[38:41], v[160:163], v[194:197], v[38:41]
	v_mfma_f32_16x16x32_bf16 v[10:13], v[168:171], v[194:197], v[10:13]
	v_mfma_f32_16x16x32_bf16 v[34:37], v[160:163], v[202:205], v[34:37]
	v_mfma_f32_16x16x32_bf16 v[14:17], v[168:171], v[202:205], v[14:17]
	v_mfma_f32_16x16x32_bf16 v[22:25], v[164:167], v[182:185], v[22:25]
	v_mfma_f32_16x16x32_bf16 v[6:9], v[174:177], v[182:185], v[6:9]
	v_mfma_f32_16x16x32_bf16 v[18:21], v[164:167], v[190:193], v[18:21]
	v_mfma_f32_16x16x32_bf16 v[2:5], v[174:177], v[190:193], v[2:5]
	v_mfma_f32_16x16x32_bf16 v[38:41], v[164:167], v[198:201], v[38:41]
	v_mfma_f32_16x16x32_bf16 v[10:13], v[174:177], v[198:201], v[10:13]
	v_mfma_f32_16x16x32_bf16 v[34:37], v[164:167], v[206:209], v[34:37]
	v_mfma_f32_16x16x32_bf16 v[14:17], v[174:177], v[206:209], v[14:17]
	s_barrier
; #define PG8_STAGE(bufoff, gbase, voff) do { _Pragma("unroll") for (int _i = 0; _i < 2; ++_i) \
;         __builtin_amdgcn_global_load_lds((const unsigned*)((const char*)(gbase) + (voff)[_i]), (PG8_LAS unsigned*)(lds + (bufoff) + ldsw + _i * 8192), 16, 0, 0); } while (0)
; #define PG8_LDA(dst, b, h) do { _Pragma("unroll") for (int m = 0; m < 4; ++m) _Pragma("unroll") for (int k = 0; k < 2; ++k) dst[m][k] = *(const PG8_LAS bf16x8*)(lds + PG8_SA(b, h) + aoff + m * 2048 + k * 1024); } while (0)
; #define PG8_MMA(ai, bj, At, Bt) do { __builtin_amdgcn_s_setprio(1); _Pragma("unroll") for (int m = 0; m < 4; ++m) _Pragma("unroll") for (int n = 0; n < 2; ++n) _Pragma("unroll") for (int k = 0; k < 2; ++k) \
;         acc[ai][bj][m][n] = __builtin_amdgcn_mfma_f32_16x16x32_bf16(Bt[n][k], At[m][k], acc[ai][bj][m][n], 0, 0, 0); __builtin_amdgcn_s_setprio(0); } while (0)
; #define PG8_WAIT_V(n) asm volatile("s_waitcnt vmcnt(" #n ")" ::: "memory")
; #define PG8_WAIT_L(n) asm volatile("s_waitcnt lgkmcnt(" #n ")" ::: "memory")
; #define PG8_BAR __builtin_amdgcn_s_barrier()
; #define PG8_SCHED __builtin_amdgcn_sched_barrier(0)
; template <class Epi, class Sched, bool ALIGN_EPI = false, bool SP2 = false>
; __device__ __forceinline__ void gemm_phase(PG8_LAS unsigned char* lds, const Gemm g, const Sched& S, const Epi& E) {
;     ...
;             if (full) PG8_LDA(At, 1, 1); PG8_STAGE(PG8_SB(1, 0), b3, voffB); PG8_STAGE(PG8_SB(1, 1), b3 + hstep, voffB); PG8_STAGE(PG8_SA(1, 0), a3, voffA);
;             PG8_WAIT_V(8); PG8_WAIT_L(0); PG8_BAR; if (full) { PG8_MMA(1, 0, At, B0); PG8_MMA(1, 1, At, B1); } PG8_BAR; PG8_SCHED;
;     ...
;         if (!has_next) break;
;         if (!Sched::KEEP || (nxt.pn >> 2) == 0) {
; #pragma unroll
;         for (int a = 0; a < 2; ++a)
; #pragma unroll
;             for (int b = 0; b < 2; ++b)
; #pragma unroll
;                 for (int m = 0; m < 4; ++m)
; #pragma unroll
;                     for (int n = 0; n < 2; ++n) acc[a][b][m][n] = (f32x4){0.f, 0.f, 0.f, 0.f};
;         }
	s_setprio 0
	s_add_i32 s34, s62, s40
	v_lshl_add_u64 v[210:211], v[210:211], 0, s[52:53]
	s_mov_b32 m0, s34
	ds_read_b128 v[178:181], v141 offset:49152
	ds_read_b128 v[182:185], v141 offset:50176
	ds_read_b128 v[186:189], v141 offset:51200
	ds_read_b128 v[190:193], v141 offset:52224
	ds_read_b128 v[194:197], v141 offset:53248
	ds_read_b128 v[198:201], v141 offset:54272
	ds_read_b128 v[202:205], v141 offset:55296
	ds_read_b128 v[206:209], v141 offset:56320
	global_load_lds_dwordx4 v[210:211], off
	s_add_i32 m0, s34, 0x2000
	s_add_u32 s30, s30, 0x40080
	v_lshl_add_u64 v[210:211], v[212:213], 0, s[52:53]
	s_addc_u32 s31, s31, 0
	s_add_i32 s34, s63, s40
	global_load_lds_dwordx4 v[210:211], off
	v_lshl_add_u64 v[210:211], s[30:31], 0, v[0:1]
	s_mov_b32 m0, s34
	s_nop 0
	global_load_lds_dwordx4 v[210:211], off
	v_lshl_add_u64 v[210:211], s[30:31], 0, v[130:131]
	s_add_i32 m0, s34, 0x2000
	s_nop 0
	global_load_lds_dwordx4 v[210:211], off
	v_lshl_add_u64 v[210:211], v[214:215], 0, s[52:53]
	s_mov_b32 m0, s48
	s_nop 0
	global_load_lds_dwordx4 v[210:211], off
	v_lshl_add_u64 v[210:211], v[220:221], 0, s[52:53]
	s_mov_b32 m0, s49
	s_nop 0
	global_load_lds_dwordx4 v[210:211], off
	s_waitcnt vmcnt(8)
	s_waitcnt lgkmcnt(0)
	s_barrier
	s_setprio 1
	s_waitcnt lgkmcnt(0)
	v_mfma_f32_16x16x32_bf16 v[102:105], v[144:147], v[178:181], v[102:105]
	v_mfma_f32_16x16x32_bf16 v[98:101], v[152:155], v[178:181], v[98:101]
	v_mfma_f32_16x16x32_bf16 v[94:97], v[144:147], v[186:189], v[94:97]
	v_mfma_f32_16x16x32_bf16 v[90:93], v[152:155], v[186:189], v[90:93]
	v_mfma_f32_16x16x32_bf16 v[78:81], v[144:147], v[194:197], v[78:81]
	v_mfma_f32_16x16x32_bf16 v[74:77], v[152:155], v[194:197], v[74:77]
	v_mfma_f32_16x16x32_bf16 v[70:73], v[144:147], v[202:205], v[70:73]
	v_mfma_f32_16x16x32_bf16 v[66:69], v[152:155], v[202:205], v[66:69]
	v_mfma_f32_16x16x32_bf16 v[102:105], v[148:151], v[182:185], v[102:105]
	v_mfma_f32_16x16x32_bf16 v[98:101], v[156:159], v[182:185], v[98:101]
	v_mfma_f32_16x16x32_bf16 v[94:97], v[148:151], v[190:193], v[94:97]
	v_mfma_f32_16x16x32_bf16 v[90:93], v[156:159], v[190:193], v[90:93]
	v_mfma_f32_16x16x32_bf16 v[78:81], v[148:151], v[198:201], v[78:81]
	v_mfma_f32_16x16x32_bf16 v[74:77], v[156:159], v[198:201], v[74:77]
	v_mfma_f32_16x16x32_bf16 v[70:73], v[148:151], v[206:209], v[70:73]
	v_mfma_f32_16x16x32_bf16 v[66:69], v[156:159], v[206:209], v[66:69]
	s_setprio 0
	s_setprio 1
	v_mfma_f32_16x16x32_bf16 v[50:53], v[160:163], v[178:181], v[50:53]
	v_mfma_f32_16x16x32_bf16 v[26:29], v[168:171], v[178:181], v[26:29]
	v_mfma_f32_16x16x32_bf16 v[46:49], v[160:163], v[186:189], v[46:49]
	v_mfma_f32_16x16x32_bf16 v[30:33], v[168:171], v[186:189], v[30:33]
	v_mfma_f32_16x16x32_bf16 v[62:65], v[160:163], v[194:197], v[62:65]
	v_mfma_f32_16x16x32_bf16 v[54:57], v[168:171], v[194:197], v[54:57]
	v_mfma_f32_16x16x32_bf16 v[58:61], v[160:163], v[202:205], v[58:61]
	v_mfma_f32_16x16x32_bf16 v[42:45], v[168:171], v[202:205], v[42:45]
	v_mfma_f32_16x16x32_bf16 v[50:53], v[164:167], v[182:185], v[50:53]
	v_mfma_f32_16x16x32_bf16 v[26:29], v[174:177], v[182:185], v[26:29]
	v_mfma_f32_16x16x32_bf16 v[46:49], v[164:167], v[190:193], v[46:49]
	v_mfma_f32_16x16x32_bf16 v[30:33], v[174:177], v[190:193], v[30:33]
	v_mfma_f32_16x16x32_bf16 v[62:65], v[164:167], v[198:201], v[62:65]
	v_mfma_f32_16x16x32_bf16 v[54:57], v[174:177], v[198:201], v[54:57]
	v_mfma_f32_16x16x32_bf16 v[58:61], v[164:167], v[206:209], v[58:61]
	v_mfma_f32_16x16x32_bf16 v[42:45], v[174:177], v[206:209], v[42:45]
	s_barrier
	s_setprio 0
	s_add_i32 s61, s61, 2
	s_add_u32 s28, s28, 0x100
	s_addc_u32 s29, s29, 0
	s_cmp_gt_u32 s61, 13
	s_cbranch_scc0 .LBB0_1149
	s_add_u32 s28, s57, 0xffffff00
	s_addc_u32 s29, s58, -1
	s_andn2_b64 vcc, exec, s[6:7]
	s_cbranch_vccnz .LBB0_1152
	v_mov_b32_e32 v42, 0
	s_mov_b32 s14, s20
	s_mov_b32 s12, s22
	s_mov_b64 s[18:19], s[26:27]
	s_mov_b32 s55, s56
	v_mov_b32_e32 v43, v42
	v_mov_b32_e32 v44, v42
	v_mov_b32_e32 v45, v42
	v_mov_b32_e32 v58, v42
	v_mov_b32_e32 v59, v42
	v_mov_b32_e32 v60, v42
	v_mov_b32_e32 v61, v42
	v_mov_b32_e32 v54, v42
	v_mov_b32_e32 v55, v42
	v_mov_b32_e32 v56, v42
	v_mov_b32_e32 v57, v42
	v_mov_b32_e32 v62, v42
	v_mov_b32_e32 v63, v42
	v_mov_b32_e32 v64, v42
	v_mov_b32_e32 v65, v42
	v_mov_b32_e32 v30, v42
	v_mov_b32_e32 v31, v42
	v_mov_b32_e32 v32, v42
	v_mov_b32_e32 v33, v42
	v_mov_b32_e32 v46, v42
	v_mov_b32_e32 v47, v42
	v_mov_b32_e32 v48, v42
	v_mov_b32_e32 v49, v42
	v_mov_b32_e32 v26, v42
	v_mov_b32_e32 v27, v42
	v_mov_b32_e32 v28, v42
	v_mov_b32_e32 v29, v42
	v_mov_b32_e32 v50, v42
	v_mov_b32_e32 v51, v42
	v_mov_b32_e32 v52, v42
	v_mov_b32_e32 v53, v42
	v_mov_b32_e32 v66, v42
	v_mov_b32_e32 v67, v42
	v_mov_b32_e32 v68, v42
	v_mov_b32_e32 v69, v42
	v_mov_b32_e32 v70, v42
	v_mov_b32_e32 v71, v42
	v_mov_b32_e32 v72, v42
	v_mov_b32_e32 v73, v42
	v_mov_b32_e32 v74, v42
	v_mov_b32_e32 v75, v42
	v_mov_b32_e32 v76, v42
	v_mov_b32_e32 v77, v42
	v_mov_b32_e32 v78, v42
	v_mov_b32_e32 v79, v42
	v_mov_b32_e32 v80, v42
	v_mov_b32_e32 v81, v42
	v_mov_b32_e32 v90, v42
	v_mov_b32_e32 v91, v42
	v_mov_b32_e32 v92, v42
	v_mov_b32_e32 v93, v42
	v_mov_b32_e32 v94, v42
	v_mov_b32_e32 v95, v42
	v_mov_b32_e32 v96, v42
	v_mov_b32_e32 v97, v42
	v_mov_b32_e32 v98, v42
	v_mov_b32_e32 v99, v42
	v_mov_b32_e32 v100, v42
	v_mov_b32_e32 v101, v42
	v_mov_b32_e32 v102, v42
	v_mov_b32_e32 v103, v42
	v_mov_b32_e32 v104, v42
	v_mov_b32_e32 v105, v42
	v_mov_b32_e32 v14, v42
	v_mov_b32_e32 v15, v42
	v_mov_b32_e32 v16, v42
	v_mov_b32_e32 v17, v42
	v_mov_b32_e32 v34, v42
	v_mov_b32_e32 v35, v42
	v_mov_b32_e32 v36, v42
	v_mov_b32_e32 v37, v42
	v_mov_b32_e32 v10, v42
	v_mov_b32_e32 v11, v42
	v_mov_b32_e32 v12, v42
	v_mov_b32_e32 v13, v42
	v_mov_b32_e32 v38, v42
	v_mov_b32_e32 v39, v42
	v_mov_b32_e32 v40, v42
	v_mov_b32_e32 v41, v42
	v_mov_b32_e32 v2, v42
	v_mov_b32_e32 v3, v42
	v_mov_b32_e32 v4, v42
	v_mov_b32_e32 v5, v42
	v_mov_b32_e32 v18, v42
	v_mov_b32_e32 v19, v42
	v_mov_b32_e32 v20, v42
	v_mov_b32_e32 v21, v42
	v_mov_b32_e32 v6, v42
	v_mov_b32_e32 v7, v42
	v_mov_b32_e32 v8, v42
	v_mov_b32_e32 v9, v42
	v_mov_b32_e32 v22, v42
	v_mov_b32_e32 v23, v42
	v_mov_b32_e32 v24, v42
	v_mov_b32_e32 v25, v42
	v_mov_b32_e32 v110, v42
	v_mov_b32_e32 v111, v42
	v_mov_b32_e32 v112, v42
	v_mov_b32_e32 v113, v42
	v_mov_b32_e32 v118, v42
	v_mov_b32_e32 v119, v42
	v_mov_b32_e32 v120, v42
	v_mov_b32_e32 v121, v42
	v_mov_b32_e32 v106, v42
	v_mov_b32_e32 v107, v42
	v_mov_b32_e32 v108, v42
	v_mov_b32_e32 v109, v42
	v_mov_b32_e32 v122, v42
	v_mov_b32_e32 v123, v42
	v_mov_b32_e32 v124, v42
	v_mov_b32_e32 v125, v42
	v_mov_b32_e32 v82, v42
	v_mov_b32_e32 v83, v42
	v_mov_b32_e32 v84, v42
	v_mov_b32_e32 v85, v42
	v_mov_b32_e32 v114, v42
	v_mov_b32_e32 v115, v42
	v_mov_b32_e32 v116, v42
	v_mov_b32_e32 v117, v42
	v_mov_b32_e32 v86, v42
	v_mov_b32_e32 v87, v42
	v_mov_b32_e32 v88, v42
	v_mov_b32_e32 v89, v42
	v_mov_b32_e32 v126, v42
	v_mov_b32_e32 v127, v42
	v_mov_b32_e32 v128, v42
	v_mov_b32_e32 v129, v42
	s_branch .LBB0_1153
